# v9 plus redundant s_nop and duplicate scratch-base SALU removed from K-loop load segments
# baseline (speedup 1.0000x reference)
; #define PG8_STAGE(bufoff, gbase, voff) do { _Pragma("unroll") for (int _i = 0; _i < 2; ++_i) \
;         __builtin_amdgcn_global_load_lds((const unsigned*)((const char*)(gbase) + (voff)[_i]), (PG8_LAS unsigned*)(lds + (bufoff) + ldsw + _i * 8192), 16, 0, 0); } while (0)
; #define PG8_LDA(dst, b, h) do { _Pragma("unroll") for (int m = 0; m < 4; ++m) _Pragma("unroll") for (int k = 0; k < 2; ++k) dst[m][k] = *(const PG8_LAS bf16x8*)(lds + PG8_SA(b, h) + aoff + m * 2048 + k * 1024); } while (0)
; #define PG8_LDB(dst, b, h) do { _Pragma("unroll") for (int n = 0; n < 2; ++n) _Pragma("unroll") for (int k = 0; k < 2; ++k) dst[n][k] = *(const PG8_LAS bf16x8*)(lds + PG8_SB(b, h) + boff + n * 2048 + k * 1024); } while (0)
; #define PG8_WAIT_V(n) asm volatile("s_waitcnt vmcnt(" #n ")" ::: "memory")
; #define PG8_WAIT_L(n) asm volatile("s_waitcnt lgkmcnt(" #n ")" ::: "memory")
; #define PG8_BAR __builtin_amdgcn_s_barrier()
; #define PG8_SCHED __builtin_amdgcn_sched_barrier(0)
;     ...
;         for (int t = 0; t < nt; t += 2) {
;             const bool last = (t == nt - 2);
;             const char* a1 = cA + (size_t)(t + 1) * kstep;
;             const char* a2 = last ? nA : cA + (size_t)(t + 2) * kstep; const char* b2 = last ? nB : cB + (size_t)(t + 2) * kstep;
;             const char* a3 = a2 + kstep; const char* b3 = b2 + kstep;
;             if (last && has_next) S.a_ready(nxt);
;             if constexpr (SP2) {
;             PG8_LDB(B0, 0, 0); PG8_LDB(B1, 0, 1); PG8_SCHED; PG8_LDA(At, 0, 0); PG8_STAGE(PG8_SA(1, 1), a1 + hstepA, voffA);
;             PG8_WAIT_V(8); PG8_WAIT_L(0); PG8_BAR; PG8_MMA(0, 0, At, B0); PG8_MMA(0, 1, At, B1); PG8_BAR; PG8_SCHED;
;             PG8_LDA(At, 0, 1); PG8_STAGE(PG8_SB(0, 0), b2, voffB); PG8_STAGE(PG8_SB(0, 1), b2 + hstepB, voffB); PG8_STAGE(PG8_SA(0, 0), a2, voffA);
;             PG8_WAIT_V(8); PG8_WAIT_L(0); PG8_BAR; PG8_MMA(1, 0, At, B0); PG8_MMA(1, 1, At, B1); PG8_BAR; PG8_SCHED;
.LBB0_538:
	v_add_u32_e32 v162, 0x10000, v153
	s_add_u32 s63, s64, 0xfffc0080
	s_addc_u32 s66, s65, -1
	s_add_i32 s68, 0, 0x10000
	s_cmp_eq_u32 s57, 12
	s_cselect_b32 s75, s6, s66
	s_cselect_b32 s74, s15, s63
	s_cselect_b32 s67, s34, s55
	s_cselect_b32 s66, s35, s45
	s_add_i32 s63, 0, 0x14000
	ds_read_b128 v[142:145], v162
	ds_read_b128 v[146:149], v162 offset:1024
	ds_read_b128 v[158:161], v162 offset:2048
	ds_read_b128 v[186:189], v162 offset:3072
	ds_read_b128 v[190:193], v162 offset:16384
	ds_read_b128 v[194:197], v162 offset:17408
	ds_read_b128 v[198:201], v162 offset:18432
	ds_read_b128 v[202:205], v162 offset:19456
	s_add_i32 m0, s81, 0xc000
	ds_read_b128 v[206:209], v156
	ds_read_b128 v[210:213], v156 offset:1024
	ds_read_b128 v[214:217], v156 offset:2048
	ds_read_b128 v[218:221], v156 offset:3072
	ds_read_b128 v[222:225], v156 offset:4096
	ds_read_b128 v[234:237], v156 offset:5120
	ds_read_b128 v[238:241], v156 offset:6144
	ds_read_b128 v[242:245], v156 offset:7168
	global_load_lds_dwordx4 v138, s[64:65]
	s_add_i32 m0, s81, 0xe000
	s_nop 0
	global_load_lds_dwordx4 v140, s[64:65]
	s_waitcnt vmcnt(8)
	s_waitcnt lgkmcnt(0)
	s_barrier
	s_setprio 1
	v_mfma_i32_16x16x64_i8 v[128:131], v[142:145], v[206:209], v[128:131]
	v_mfma_i32_16x16x64_i8 v[120:123], v[158:161], v[206:209], v[120:123]
	v_mfma_i32_16x16x64_i8 v[112:115], v[142:145], v[214:217], v[112:115]
	v_mfma_i32_16x16x64_i8 v[104:107], v[158:161], v[214:217], v[104:107]
	v_mfma_i32_16x16x64_i8 v[96:99], v[142:145], v[222:225], v[96:99]
	v_mfma_i32_16x16x64_i8 v[88:91], v[158:161], v[222:225], v[88:91]
	v_mfma_i32_16x16x64_i8 v[80:83], v[142:145], v[238:241], v[80:83]
	v_mfma_i32_16x16x64_i8 v[72:75], v[158:161], v[238:241], v[72:75]
	v_mfma_i32_16x16x64_i8 v[128:131], v[146:149], v[210:213], v[128:131]
	v_mfma_i32_16x16x64_i8 v[120:123], v[186:189], v[210:213], v[120:123]
	v_mfma_i32_16x16x64_i8 v[112:115], v[146:149], v[218:221], v[112:115]
	v_mfma_i32_16x16x64_i8 v[104:107], v[186:189], v[218:221], v[104:107]
	v_mfma_i32_16x16x64_i8 v[96:99], v[146:149], v[234:237], v[96:99]
	v_mfma_i32_16x16x64_i8 v[88:91], v[186:189], v[234:237], v[88:91]
	v_mfma_i32_16x16x64_i8 v[80:83], v[146:149], v[242:245], v[80:83]
	v_mfma_i32_16x16x64_i8 v[72:75], v[186:189], v[242:245], v[72:75]
	v_mfma_i32_16x16x64_i8 v[124:127], v[190:193], v[206:209], v[124:127]
	v_mfma_i32_16x16x64_i8 v[116:119], v[198:201], v[206:209], v[116:119]
	v_mfma_i32_16x16x64_i8 v[108:111], v[190:193], v[214:217], v[108:111]
	v_mfma_i32_16x16x64_i8 v[100:103], v[198:201], v[214:217], v[100:103]
	v_mfma_i32_16x16x64_i8 v[92:95], v[190:193], v[222:225], v[92:95]
	v_mfma_i32_16x16x64_i8 v[84:87], v[198:201], v[222:225], v[84:87]
	v_mfma_i32_16x16x64_i8 v[76:79], v[190:193], v[238:241], v[76:79]
	v_mfma_i32_16x16x64_i8 v[68:71], v[198:201], v[238:241], v[68:71]
	v_mfma_i32_16x16x64_i8 v[124:127], v[194:197], v[210:213], v[124:127]
	v_mfma_i32_16x16x64_i8 v[116:119], v[202:205], v[210:213], v[116:119]
	v_mfma_i32_16x16x64_i8 v[108:111], v[194:197], v[218:221], v[108:111]
	v_mfma_i32_16x16x64_i8 v[100:103], v[202:205], v[218:221], v[100:103]
	v_mfma_i32_16x16x64_i8 v[92:95], v[194:197], v[234:237], v[92:95]
	v_mfma_i32_16x16x64_i8 v[84:87], v[202:205], v[234:237], v[84:87]
	v_mfma_i32_16x16x64_i8 v[76:79], v[194:197], v[242:245], v[76:79]
	v_mfma_i32_16x16x64_i8 v[68:71], v[202:205], v[242:245], v[68:71]
	s_setprio 0
	s_barrier
	s_add_i32 s68, s68, s10
	s_mov_b32 m0, s68
	ds_read_b128 v[206:209], v156 offset:16384
	ds_read_b128 v[210:213], v156 offset:17408
	ds_read_b128 v[214:217], v156 offset:18432
	ds_read_b128 v[218:221], v156 offset:19456
	ds_read_b128 v[222:225], v156 offset:20480
	ds_read_b128 v[234:237], v156 offset:21504
	ds_read_b128 v[238:241], v156 offset:22528
	ds_read_b128 v[242:245], v156 offset:23552
	global_load_lds_dwordx4 v34, s[66:67]
	s_add_i32 m0, s68, 0x2000
	s_add_u32 s70, s66, 0x40000
	s_addc_u32 s71, s67, 0
	s_add_i32 s63, s63, s10
	global_load_lds_dwordx4 v136, s[66:67]
	s_mov_b32 m0, s63
	s_nop 0
	global_load_lds_dwordx4 v34, s[70:71]
	s_add_i32 m0, s63, 0x2000
	s_nop 0
	global_load_lds_dwordx4 v136, s[70:71]
	s_mov_b32 m0, s81
	s_nop 0
	global_load_lds_dwordx4 v132, s[74:75]
	s_mov_b32 m0, s82
	s_nop 0
	global_load_lds_dwordx4 v134, s[74:75]
	s_waitcnt vmcnt(8)
	s_waitcnt lgkmcnt(0)
	s_barrier
	s_setprio 1
	v_mfma_i32_16x16x64_i8 v[64:67], v[142:145], v[206:209], v[64:67]
	v_mfma_i32_16x16x64_i8 v[56:59], v[158:161], v[206:209], v[56:59]
	v_mfma_i32_16x16x64_i8 v[48:51], v[142:145], v[214:217], v[48:51]
	v_mfma_i32_16x16x64_i8 v[40:43], v[158:161], v[214:217], v[40:43]
	v_mfma_i32_16x16x64_i8 v[30:33], v[142:145], v[222:225], v[30:33]
	v_mfma_i32_16x16x64_i8 v[22:25], v[158:161], v[222:225], v[22:25]
	v_mfma_i32_16x16x64_i8 v[14:17], v[142:145], v[238:241], v[14:17]
	v_mfma_i32_16x16x64_i8 v[6:9], v[158:161], v[238:241], v[6:9]
	v_mfma_i32_16x16x64_i8 v[64:67], v[146:149], v[210:213], v[64:67]
	v_mfma_i32_16x16x64_i8 v[56:59], v[186:189], v[210:213], v[56:59]
	v_mfma_i32_16x16x64_i8 v[48:51], v[146:149], v[218:221], v[48:51]
	v_mfma_i32_16x16x64_i8 v[40:43], v[186:189], v[218:221], v[40:43]
	v_mfma_i32_16x16x64_i8 v[30:33], v[146:149], v[234:237], v[30:33]
	v_mfma_i32_16x16x64_i8 v[22:25], v[186:189], v[234:237], v[22:25]
	v_mfma_i32_16x16x64_i8 v[14:17], v[146:149], v[242:245], v[14:17]
	v_mfma_i32_16x16x64_i8 v[6:9], v[186:189], v[242:245], v[6:9]
	v_mfma_i32_16x16x64_i8 v[60:63], v[190:193], v[206:209], v[60:63]
	v_mfma_i32_16x16x64_i8 v[52:55], v[198:201], v[206:209], v[52:55]
	v_mfma_i32_16x16x64_i8 v[44:47], v[190:193], v[214:217], v[44:47]
	v_mfma_i32_16x16x64_i8 v[36:39], v[198:201], v[214:217], v[36:39]
	v_mfma_i32_16x16x64_i8 v[26:29], v[190:193], v[222:225], v[26:29]
	v_mfma_i32_16x16x64_i8 v[18:21], v[198:201], v[222:225], v[18:21]
	v_mfma_i32_16x16x64_i8 v[10:13], v[190:193], v[238:241], v[10:13]
	v_mfma_i32_16x16x64_i8 v[2:5], v[198:201], v[238:241], v[2:5]
	v_mfma_i32_16x16x64_i8 v[60:63], v[194:197], v[210:213], v[60:63]
	v_mfma_i32_16x16x64_i8 v[52:55], v[202:205], v[210:213], v[52:55]
	v_mfma_i32_16x16x64_i8 v[44:47], v[194:197], v[218:221], v[44:47]
	v_mfma_i32_16x16x64_i8 v[36:39], v[202:205], v[218:221], v[36:39]
	v_mfma_i32_16x16x64_i8 v[26:29], v[194:197], v[234:237], v[26:29]
	v_mfma_i32_16x16x64_i8 v[18:21], v[202:205], v[234:237], v[18:21]
	v_mfma_i32_16x16x64_i8 v[10:13], v[194:197], v[242:245], v[10:13]
	v_mfma_i32_16x16x64_i8 v[2:5], v[202:205], v[242:245], v[2:5]
	s_setprio 0
	s_barrier
; #define PG8_STAGE(bufoff, gbase, voff) do { _Pragma("unroll") for (int _i = 0; _i < 2; ++_i) \
;         __builtin_amdgcn_global_load_lds((const unsigned*)((const char*)(gbase) + (voff)[_i]), (PG8_LAS unsigned*)(lds + (bufoff) + ldsw + _i * 8192), 16, 0, 0); } while (0)
; #define PG8_LDA(dst, b, h) do { _Pragma("unroll") for (int m = 0; m < 4; ++m) _Pragma("unroll") for (int k = 0; k < 2; ++k) dst[m][k] = *(const PG8_LAS bf16x8*)(lds + PG8_SA(b, h) + aoff + m * 2048 + k * 1024); } while (0)
; #define PG8_LDB(dst, b, h) do { _Pragma("unroll") for (int n = 0; n < 2; ++n) _Pragma("unroll") for (int k = 0; k < 2; ++k) dst[n][k] = *(const PG8_LAS bf16x8*)(lds + PG8_SB(b, h) + boff + n * 2048 + k * 1024); } while (0)
; #define PG8_WAIT_V(n) asm volatile("s_waitcnt vmcnt(" #n ")" ::: "memory")
; #define PG8_WAIT_L(n) asm volatile("s_waitcnt lgkmcnt(" #n ")" ::: "memory")
; #define PG8_BAR __builtin_amdgcn_s_barrier()
; #define PG8_SCHED __builtin_amdgcn_sched_barrier(0)
;     ...
;             PG8_LDB(B0, 1, 0); PG8_LDB(B1, 1, 1); PG8_SCHED; PG8_LDA(At, 1, 0); PG8_STAGE(PG8_SA(0, 1), a2 + hstepA, voffA);
;             PG8_WAIT_V(8); PG8_WAIT_L(0); PG8_BAR; PG8_MMA(0, 0, At, B0); PG8_MMA(0, 1, At, B1); PG8_BAR; PG8_SCHED;
	s_add_i32 s63, 0, 0x18000
	s_add_i32 s68, 0, 0x1c000
	ds_read_b128 v[142:145], v162 offset:32768
	ds_read_b128 v[146:149], v162 offset:33792
	ds_read_b128 v[158:161], v162 offset:34816
	ds_read_b128 v[186:189], v162 offset:35840
	ds_read_b128 v[190:193], v162 offset:49152
	ds_read_b128 v[194:197], v162 offset:50176
	ds_read_b128 v[198:201], v162 offset:51200
	ds_read_b128 v[202:205], v162 offset:52224
	s_add_u32 s70, s74, 0x40000
	s_addc_u32 s71, s75, 0
	s_mov_b32 m0, s83
	ds_read_b128 v[206:209], v156 offset:32768
	ds_read_b128 v[210:213], v156 offset:33792
	ds_read_b128 v[214:217], v156 offset:34816
	ds_read_b128 v[218:221], v156 offset:35840
	ds_read_b128 v[222:225], v156 offset:36864
	ds_read_b128 v[234:237], v156 offset:37888
	ds_read_b128 v[238:241], v156 offset:38912
	ds_read_b128 v[242:245], v156 offset:39936
	global_load_lds_dwordx4 v132, s[70:71]
	s_mov_b32 m0, s84
	s_nop 0
	global_load_lds_dwordx4 v134, s[70:71]
	s_waitcnt vmcnt(8)
	s_waitcnt lgkmcnt(0)
	s_barrier
	s_setprio 1
	v_mfma_i32_16x16x64_i8 v[128:131], v[142:145], v[206:209], v[128:131]
	v_mfma_i32_16x16x64_i8 v[120:123], v[158:161], v[206:209], v[120:123]
	v_mfma_i32_16x16x64_i8 v[112:115], v[142:145], v[214:217], v[112:115]
	v_mfma_i32_16x16x64_i8 v[104:107], v[158:161], v[214:217], v[104:107]
	v_mfma_i32_16x16x64_i8 v[96:99], v[142:145], v[222:225], v[96:99]
	v_mfma_i32_16x16x64_i8 v[88:91], v[158:161], v[222:225], v[88:91]
	v_mfma_i32_16x16x64_i8 v[80:83], v[142:145], v[238:241], v[80:83]
	v_mfma_i32_16x16x64_i8 v[72:75], v[158:161], v[238:241], v[72:75]
	v_mfma_i32_16x16x64_i8 v[128:131], v[146:149], v[210:213], v[128:131]
	v_mfma_i32_16x16x64_i8 v[120:123], v[186:189], v[210:213], v[120:123]
	v_mfma_i32_16x16x64_i8 v[112:115], v[146:149], v[218:221], v[112:115]
	v_mfma_i32_16x16x64_i8 v[104:107], v[186:189], v[218:221], v[104:107]
	v_mfma_i32_16x16x64_i8 v[96:99], v[146:149], v[234:237], v[96:99]
	v_mfma_i32_16x16x64_i8 v[88:91], v[186:189], v[234:237], v[88:91]
	v_mfma_i32_16x16x64_i8 v[80:83], v[146:149], v[242:245], v[80:83]
	v_mfma_i32_16x16x64_i8 v[72:75], v[186:189], v[242:245], v[72:75]
	v_mfma_i32_16x16x64_i8 v[124:127], v[190:193], v[206:209], v[124:127]
	v_mfma_i32_16x16x64_i8 v[116:119], v[198:201], v[206:209], v[116:119]
	v_mfma_i32_16x16x64_i8 v[108:111], v[190:193], v[214:217], v[108:111]
	v_mfma_i32_16x16x64_i8 v[100:103], v[198:201], v[214:217], v[100:103]
	v_mfma_i32_16x16x64_i8 v[92:95], v[190:193], v[222:225], v[92:95]
	v_mfma_i32_16x16x64_i8 v[84:87], v[198:201], v[222:225], v[84:87]
	v_mfma_i32_16x16x64_i8 v[76:79], v[190:193], v[238:241], v[76:79]
	v_mfma_i32_16x16x64_i8 v[68:71], v[198:201], v[238:241], v[68:71]
	v_mfma_i32_16x16x64_i8 v[124:127], v[194:197], v[210:213], v[124:127]
	v_mfma_i32_16x16x64_i8 v[116:119], v[202:205], v[210:213], v[116:119]
	v_mfma_i32_16x16x64_i8 v[108:111], v[194:197], v[218:221], v[108:111]
	v_mfma_i32_16x16x64_i8 v[100:103], v[202:205], v[218:221], v[100:103]
	v_mfma_i32_16x16x64_i8 v[92:95], v[194:197], v[234:237], v[92:95]
	v_mfma_i32_16x16x64_i8 v[84:87], v[202:205], v[234:237], v[84:87]
	v_mfma_i32_16x16x64_i8 v[76:79], v[194:197], v[242:245], v[76:79]
	v_mfma_i32_16x16x64_i8 v[68:71], v[202:205], v[242:245], v[68:71]
	s_setprio 0
	s_barrier
; #define PG8_STAGE(bufoff, gbase, voff) do { _Pragma("unroll") for (int _i = 0; _i < 2; ++_i) \
;         __builtin_amdgcn_global_load_lds((const unsigned*)((const char*)(gbase) + (voff)[_i]), (PG8_LAS unsigned*)(lds + (bufoff) + ldsw + _i * 8192), 16, 0, 0); } while (0)
; #define PG8_LDA(dst, b, h) do { _Pragma("unroll") for (int m = 0; m < 4; ++m) _Pragma("unroll") for (int k = 0; k < 2; ++k) dst[m][k] = *(const PG8_LAS bf16x8*)(lds + PG8_SA(b, h) + aoff + m * 2048 + k * 1024); } while (0)
; #define PG8_WAIT_V(n) asm volatile("s_waitcnt vmcnt(" #n ")" ::: "memory")
; #define PG8_WAIT_L(n) asm volatile("s_waitcnt lgkmcnt(" #n ")" ::: "memory")
; #define PG8_BAR __builtin_amdgcn_s_barrier()
; #define PG8_SCHED __builtin_amdgcn_sched_barrier(0)
;     __device__ __forceinline__ void operator()(const f32x4 (&acc)[2][2][4][2], const Unit& u, int wr, int wc, int fr, int fq) const {
;     ...
;                 float r[8]; const float scr_ = rs ? rs[row0 + ai * HALF + m * 16] * sc : sc;
;     ...
;             PG8_LDA(At, 1, 1); PG8_STAGE(PG8_SB(1, 0), b3, voffB); PG8_STAGE(PG8_SB(1, 1), b3 + hstepB, voffB); PG8_STAGE(PG8_SA(1, 0), a3, voffA);
;             PG8_WAIT_V(8); PG8_WAIT_L(0); PG8_BAR; PG8_MMA(1, 0, At, B0); PG8_MMA(1, 1, At, B1); PG8_BAR; PG8_SCHED;
	s_add_i32 s63, s63, s10
	s_mov_b32 m0, s63
	ds_read_b128 v[206:209], v156 offset:49152
	ds_read_b128 v[210:213], v156 offset:50176
	ds_read_b128 v[214:217], v156 offset:51200
	ds_read_b128 v[218:221], v156 offset:52224
	ds_read_b128 v[222:225], v156 offset:53248
	ds_read_b128 v[234:237], v156 offset:54272
	ds_read_b128 v[238:241], v156 offset:55296
	ds_read_b128 v[242:245], v156 offset:56320
	s_add_u32 vcc_lo, s66, 0x80
	s_addc_u32 vcc_hi, s67, 0
	global_load_lds_dwordx4 v34, vcc
	s_add_i32 m0, s63, 0x2000
	s_add_u32 s66, s66, 0x40080
	s_addc_u32 s67, s67, 0
	s_add_i32 s63, s68, s10
	s_add_u32 vcc_lo, s66, 0xfffc0000
	s_addc_u32 vcc_hi, s67, -1
	global_load_lds_dwordx4 v136, vcc
	s_mov_b32 m0, s63
	s_nop 0
	global_load_lds_dwordx4 v34, s[66:67]
	s_add_i32 m0, s63, 0x2000
	s_nop 0
	global_load_lds_dwordx4 v136, s[66:67]
	s_mov_b32 m0, s86
	s_add_u32 vcc_lo, s74, 0x80
	s_addc_u32 vcc_hi, s75, 0
	global_load_lds_dwordx4 v132, vcc
	s_mov_b32 m0, s87
	s_nop 0
	global_load_lds_dwordx4 v134, vcc
	s_waitcnt vmcnt(8)
	s_waitcnt lgkmcnt(0)
	s_barrier
	s_setprio 1
	v_mfma_i32_16x16x64_i8 v[64:67], v[142:145], v[206:209], v[64:67]
	v_mfma_i32_16x16x64_i8 v[56:59], v[158:161], v[206:209], v[56:59]
	v_mfma_i32_16x16x64_i8 v[48:51], v[142:145], v[214:217], v[48:51]
	v_mfma_i32_16x16x64_i8 v[40:43], v[158:161], v[214:217], v[40:43]
	v_mfma_i32_16x16x64_i8 v[30:33], v[142:145], v[222:225], v[30:33]
	v_mfma_i32_16x16x64_i8 v[22:25], v[158:161], v[222:225], v[22:25]
	v_mfma_i32_16x16x64_i8 v[14:17], v[142:145], v[238:241], v[14:17]
	v_mfma_i32_16x16x64_i8 v[6:9], v[158:161], v[238:241], v[6:9]
	v_mfma_i32_16x16x64_i8 v[64:67], v[146:149], v[210:213], v[64:67]
	v_mfma_i32_16x16x64_i8 v[56:59], v[186:189], v[210:213], v[56:59]
	v_mfma_i32_16x16x64_i8 v[48:51], v[146:149], v[218:221], v[48:51]
	v_mfma_i32_16x16x64_i8 v[40:43], v[186:189], v[218:221], v[40:43]
	v_mfma_i32_16x16x64_i8 v[30:33], v[146:149], v[234:237], v[30:33]
	v_mfma_i32_16x16x64_i8 v[22:25], v[186:189], v[234:237], v[22:25]
	v_mfma_i32_16x16x64_i8 v[14:17], v[146:149], v[242:245], v[14:17]
	v_mfma_i32_16x16x64_i8 v[6:9], v[186:189], v[242:245], v[6:9]
	v_mfma_i32_16x16x64_i8 v[60:63], v[190:193], v[206:209], v[60:63]
	v_mfma_i32_16x16x64_i8 v[52:55], v[198:201], v[206:209], v[52:55]
	v_mfma_i32_16x16x64_i8 v[44:47], v[190:193], v[214:217], v[44:47]
	v_mfma_i32_16x16x64_i8 v[36:39], v[198:201], v[214:217], v[36:39]
	v_mfma_i32_16x16x64_i8 v[26:29], v[190:193], v[222:225], v[26:29]
	v_mfma_i32_16x16x64_i8 v[18:21], v[198:201], v[222:225], v[18:21]
	v_mfma_i32_16x16x64_i8 v[10:13], v[190:193], v[238:241], v[10:13]
	v_mfma_i32_16x16x64_i8 v[2:5], v[198:201], v[238:241], v[2:5]
	v_mfma_i32_16x16x64_i8 v[60:63], v[194:197], v[210:213], v[60:63]
	v_mfma_i32_16x16x64_i8 v[52:55], v[202:205], v[210:213], v[52:55]
	v_mfma_i32_16x16x64_i8 v[44:47], v[194:197], v[218:221], v[44:47]
	v_mfma_i32_16x16x64_i8 v[36:39], v[202:205], v[218:221], v[36:39]
	v_mfma_i32_16x16x64_i8 v[26:29], v[194:197], v[234:237], v[26:29]
	v_mfma_i32_16x16x64_i8 v[18:21], v[202:205], v[234:237], v[18:21]
	v_mfma_i32_16x16x64_i8 v[10:13], v[194:197], v[242:245], v[10:13]
	v_mfma_i32_16x16x64_i8 v[2:5], v[202:205], v[242:245], v[2:5]
	s_setprio 0
	s_barrier
	s_add_i32 s57, s57, 2
	s_add_u32 s64, s64, 0x100
	s_addc_u32 s65, s65, 0
	s_add_u32 s45, s45, 0x100
	s_addc_u32 s55, s55, 0
	s_cmp_gt_u32 s57, 13
	s_cbranch_scc0 .LBB0_538
	v_lshl_add_u32 v144, s62, 8, v152
	v_ashrrev_i32_e32 v145, 31, v144
	v_lshl_add_u64 v[146:147], v[144:145], 2, s[50:51]
	global_load_dword v186, v[146:147], off
	global_load_dword v187, v[146:147], off offset:64
	global_load_dword v188, v[146:147], off offset:128
	global_load_dword v189, v[146:147], off offset:192
	global_load_dword v190, v[146:147], off offset:512
	global_load_dword v191, v[146:147], off offset:576
	global_load_dword v192, v[146:147], off offset:640
	global_load_dword v193, v[146:147], off offset:704
	s_and_b64 vcc, exec, s[52:53]
	s_cbranch_vccz .LBB0_541
	s_barrier

; #define PG8_STAGE(bufoff, gbase, voff) do { _Pragma("unroll") for (int _i = 0; _i < 2; ++_i) \
;         __builtin_amdgcn_global_load_lds((const unsigned*)((const char*)(gbase) + (voff)[_i]), (PG8_LAS unsigned*)(lds + (bufoff) + ldsw + _i * 8192), 16, 0, 0); } while (0)
; #define PG8_LDA(dst, b, h) do { _Pragma("unroll") for (int m = 0; m < 4; ++m) _Pragma("unroll") for (int k = 0; k < 2; ++k) dst[m][k] = *(const PG8_LAS bf16x8*)(lds + PG8_SA(b, h) + aoff + m * 2048 + k * 1024); } while (0)
; #define PG8_LDB(dst, b, h) do { _Pragma("unroll") for (int n = 0; n < 2; ++n) _Pragma("unroll") for (int k = 0; k < 2; ++k) dst[n][k] = *(const PG8_LAS bf16x8*)(lds + PG8_SB(b, h) + boff + n * 2048 + k * 1024); } while (0)
; #define PG8_WAIT_V(n) asm volatile("s_waitcnt vmcnt(" #n ")" ::: "memory")
; #define PG8_WAIT_L(n) asm volatile("s_waitcnt lgkmcnt(" #n ")" ::: "memory")
; #define PG8_BAR __builtin_amdgcn_s_barrier()
; #define PG8_SCHED __builtin_amdgcn_sched_barrier(0)
;     ...
;         for (int t = 0; t < nt; t += 2) {
;             const bool last = (t == nt - 2);
;             const char* a1 = cA + (size_t)(t + 1) * kstep;
;             const char* a2 = last ? nA : cA + (size_t)(t + 2) * kstep; const char* b2 = last ? nB : cB + (size_t)(t + 2) * kstep;
;             const char* a3 = a2 + kstep; const char* b3 = b2 + kstep;
;             if (last && has_next) S.a_ready(nxt);
;             if constexpr (SP2) {
;             PG8_LDB(B0, 0, 0); PG8_LDB(B1, 0, 1); PG8_SCHED; PG8_LDA(At, 0, 0); PG8_STAGE(PG8_SA(1, 1), a1 + hstepA, voffA);
;             PG8_WAIT_V(8); PG8_WAIT_L(0); PG8_BAR; PG8_MMA(0, 0, At, B0); PG8_MMA(0, 1, At, B1); PG8_BAR; PG8_SCHED;
;             PG8_LDA(At, 0, 1); PG8_STAGE(PG8_SB(0, 0), b2, voffB); PG8_STAGE(PG8_SB(0, 1), b2 + hstepB, voffB); PG8_STAGE(PG8_SA(0, 0), a2, voffA);
;             PG8_WAIT_V(8); PG8_WAIT_L(0); PG8_BAR; PG8_MMA(1, 0, At, B0); PG8_MMA(1, 1, At, B1); PG8_BAR; PG8_SCHED;
.LBB0_694:
	v_add_u32_e32 v163, 0x10000, v143
	s_add_u32 s44, s42, 0x100
	s_addc_u32 s45, s43, 0
	s_add_i32 s67, 0, 0x10000
	s_cmpk_eq_i32 s66, 0x54
	s_cselect_b32 s53, s37, s45
	s_cselect_b32 s52, s36, s44
	s_cselect_b32 s51, s41, s65
	s_cselect_b32 s50, s40, s64
	s_add_i32 s68, 0, 0x14000
	ds_read_b128 v[146:149], v163
	ds_read_b128 v[150:153], v163 offset:1024
	ds_read_b128 v[154:157], v163 offset:2048
	ds_read_b128 v[158:161], v163 offset:3072
	ds_read_b128 v[186:189], v163 offset:16384
	ds_read_b128 v[190:193], v163 offset:17408
	ds_read_b128 v[194:197], v163 offset:18432
	ds_read_b128 v[198:201], v163 offset:19456
	s_add_i32 m0, s34, 0xc000
	ds_read_b128 v[202:205], v145
	ds_read_b128 v[206:209], v145 offset:1024
	ds_read_b128 v[210:213], v145 offset:2048
	ds_read_b128 v[214:217], v145 offset:3072
	ds_read_b128 v[218:221], v145 offset:4096
	ds_read_b128 v[222:225], v145 offset:5120
	ds_read_b128 v[234:237], v145 offset:6144
	ds_read_b128 v[238:241], v145 offset:7168
	global_load_lds_dwordx4 v138, s[42:43]
	s_add_i32 m0, s34, 0xe000
	s_nop 0
	global_load_lds_dwordx4 v140, s[42:43]
	s_waitcnt vmcnt(8)
	s_waitcnt lgkmcnt(0)
	s_barrier
	s_setprio 1
	v_mfma_f32_16x16x32_bf16 v[128:131], v[146:149], v[202:205], v[128:131]
	v_mfma_f32_16x16x32_bf16 v[124:127], v[154:157], v[202:205], v[124:127]
	v_mfma_f32_16x16x32_bf16 v[120:123], v[146:149], v[210:213], v[120:123]
	v_mfma_f32_16x16x32_bf16 v[116:119], v[154:157], v[210:213], v[116:119]
	v_mfma_f32_16x16x32_bf16 v[104:107], v[146:149], v[218:221], v[104:107]
	v_mfma_f32_16x16x32_bf16 v[100:103], v[154:157], v[218:221], v[100:103]
	v_mfma_f32_16x16x32_bf16 v[88:91], v[146:149], v[234:237], v[88:91]
	v_mfma_f32_16x16x32_bf16 v[84:87], v[154:157], v[234:237], v[84:87]
	v_mfma_f32_16x16x32_bf16 v[128:131], v[150:153], v[206:209], v[128:131]
	v_mfma_f32_16x16x32_bf16 v[124:127], v[158:161], v[206:209], v[124:127]
	v_mfma_f32_16x16x32_bf16 v[120:123], v[150:153], v[214:217], v[120:123]
	v_mfma_f32_16x16x32_bf16 v[116:119], v[158:161], v[214:217], v[116:119]
	v_mfma_f32_16x16x32_bf16 v[104:107], v[150:153], v[222:225], v[104:107]
	v_mfma_f32_16x16x32_bf16 v[100:103], v[158:161], v[222:225], v[100:103]
	v_mfma_f32_16x16x32_bf16 v[88:91], v[150:153], v[238:241], v[88:91]
	v_mfma_f32_16x16x32_bf16 v[84:87], v[158:161], v[238:241], v[84:87]
	v_mfma_f32_16x16x32_bf16 v[112:115], v[186:189], v[202:205], v[112:115]
	v_mfma_f32_16x16x32_bf16 v[108:111], v[194:197], v[202:205], v[108:111]
	v_mfma_f32_16x16x32_bf16 v[96:99], v[186:189], v[210:213], v[96:99]
	v_mfma_f32_16x16x32_bf16 v[92:95], v[194:197], v[210:213], v[92:95]
	v_mfma_f32_16x16x32_bf16 v[80:83], v[186:189], v[218:221], v[80:83]
	v_mfma_f32_16x16x32_bf16 v[76:79], v[194:197], v[218:221], v[76:79]
	v_mfma_f32_16x16x32_bf16 v[72:75], v[186:189], v[234:237], v[72:75]
	v_mfma_f32_16x16x32_bf16 v[68:71], v[194:197], v[234:237], v[68:71]
	v_mfma_f32_16x16x32_bf16 v[112:115], v[190:193], v[206:209], v[112:115]
	v_mfma_f32_16x16x32_bf16 v[108:111], v[198:201], v[206:209], v[108:111]
	v_mfma_f32_16x16x32_bf16 v[96:99], v[190:193], v[214:217], v[96:99]
	v_mfma_f32_16x16x32_bf16 v[92:95], v[198:201], v[214:217], v[92:95]
	v_mfma_f32_16x16x32_bf16 v[80:83], v[190:193], v[222:225], v[80:83]
	v_mfma_f32_16x16x32_bf16 v[76:79], v[198:201], v[222:225], v[76:79]
	v_mfma_f32_16x16x32_bf16 v[72:75], v[190:193], v[238:241], v[72:75]
	v_mfma_f32_16x16x32_bf16 v[68:71], v[198:201], v[238:241], v[68:71]
	s_setprio 0
	s_barrier
	s_add_i32 s42, s67, s15
	s_mov_b32 m0, s42
	ds_read_b128 v[202:205], v145 offset:16384
	ds_read_b128 v[206:209], v145 offset:17408
	ds_read_b128 v[210:213], v145 offset:18432
	ds_read_b128 v[214:217], v145 offset:19456
	ds_read_b128 v[218:221], v145 offset:20480
	ds_read_b128 v[222:225], v145 offset:21504
	ds_read_b128 v[234:237], v145 offset:22528
	ds_read_b128 v[238:241], v145 offset:23552
	global_load_lds_dwordx4 v34, s[50:51]
	s_add_i32 m0, s42, 0x2000
	s_add_u32 s42, s50, 0x160000
	s_addc_u32 s43, s51, 0
	s_add_u32 s98, s50, 0x80
	s_addc_u32 s99, s51, 0
	s_add_i32 s67, s68, s15
	global_load_lds_dwordx4 v136, s[50:51]
	s_mov_b32 m0, s67
	s_nop 0
	global_load_lds_dwordx4 v34, s[42:43]
	s_add_i32 m0, s67, 0x2000
	s_nop 0
	global_load_lds_dwordx4 v136, s[42:43]
	s_mov_b32 m0, s34
	s_nop 0
	global_load_lds_dwordx4 v132, s[52:53]
	s_mov_b32 m0, s35
	s_nop 0
	global_load_lds_dwordx4 v134, s[52:53]
	s_waitcnt vmcnt(8)
	s_waitcnt lgkmcnt(0)
	s_barrier
	s_setprio 1
	v_mfma_f32_16x16x32_bf16 v[64:67], v[146:149], v[202:205], v[64:67]
	v_mfma_f32_16x16x32_bf16 v[60:63], v[154:157], v[202:205], v[60:63]
	v_mfma_f32_16x16x32_bf16 v[56:59], v[146:149], v[210:213], v[56:59]
	v_mfma_f32_16x16x32_bf16 v[52:55], v[154:157], v[210:213], v[52:55]
	v_mfma_f32_16x16x32_bf16 v[40:43], v[146:149], v[218:221], v[40:43]
	v_mfma_f32_16x16x32_bf16 v[36:39], v[154:157], v[218:221], v[36:39]
	v_mfma_f32_16x16x32_bf16 v[22:25], v[146:149], v[234:237], v[22:25]
	v_mfma_f32_16x16x32_bf16 v[18:21], v[154:157], v[234:237], v[18:21]
	v_mfma_f32_16x16x32_bf16 v[64:67], v[150:153], v[206:209], v[64:67]
	v_mfma_f32_16x16x32_bf16 v[60:63], v[158:161], v[206:209], v[60:63]
	v_mfma_f32_16x16x32_bf16 v[56:59], v[150:153], v[214:217], v[56:59]
	v_mfma_f32_16x16x32_bf16 v[52:55], v[158:161], v[214:217], v[52:55]
	v_mfma_f32_16x16x32_bf16 v[40:43], v[150:153], v[222:225], v[40:43]
	v_mfma_f32_16x16x32_bf16 v[36:39], v[158:161], v[222:225], v[36:39]
	v_mfma_f32_16x16x32_bf16 v[22:25], v[150:153], v[238:241], v[22:25]
	v_mfma_f32_16x16x32_bf16 v[18:21], v[158:161], v[238:241], v[18:21]
	v_mfma_f32_16x16x32_bf16 v[48:51], v[186:189], v[202:205], v[48:51]
	v_mfma_f32_16x16x32_bf16 v[44:47], v[194:197], v[202:205], v[44:47]
	v_mfma_f32_16x16x32_bf16 v[30:33], v[186:189], v[210:213], v[30:33]
	v_mfma_f32_16x16x32_bf16 v[26:29], v[194:197], v[210:213], v[26:29]
	v_mfma_f32_16x16x32_bf16 v[14:17], v[186:189], v[218:221], v[14:17]
	v_mfma_f32_16x16x32_bf16 v[10:13], v[194:197], v[218:221], v[10:13]
	v_mfma_f32_16x16x32_bf16 v[6:9], v[186:189], v[234:237], v[6:9]
	v_mfma_f32_16x16x32_bf16 v[2:5], v[194:197], v[234:237], v[2:5]
	v_mfma_f32_16x16x32_bf16 v[48:51], v[190:193], v[206:209], v[48:51]
	v_mfma_f32_16x16x32_bf16 v[44:47], v[198:201], v[206:209], v[44:47]
	v_mfma_f32_16x16x32_bf16 v[30:33], v[190:193], v[214:217], v[30:33]
	v_mfma_f32_16x16x32_bf16 v[26:29], v[198:201], v[214:217], v[26:29]
	v_mfma_f32_16x16x32_bf16 v[14:17], v[190:193], v[222:225], v[14:17]
	v_mfma_f32_16x16x32_bf16 v[10:13], v[198:201], v[222:225], v[10:13]
	v_mfma_f32_16x16x32_bf16 v[6:9], v[190:193], v[238:241], v[6:9]
	v_mfma_f32_16x16x32_bf16 v[2:5], v[198:201], v[238:241], v[2:5]
	s_setprio 0
	s_barrier
; #define PG8_STAGE(bufoff, gbase, voff) do { _Pragma("unroll") for (int _i = 0; _i < 2; ++_i) \
;         __builtin_amdgcn_global_load_lds((const unsigned*)((const char*)(gbase) + (voff)[_i]), (PG8_LAS unsigned*)(lds + (bufoff) + ldsw + _i * 8192), 16, 0, 0); } while (0)
; #define PG8_LDA(dst, b, h) do { _Pragma("unroll") for (int m = 0; m < 4; ++m) _Pragma("unroll") for (int k = 0; k < 2; ++k) dst[m][k] = *(const PG8_LAS bf16x8*)(lds + PG8_SA(b, h) + aoff + m * 2048 + k * 1024); } while (0)
; #define PG8_LDB(dst, b, h) do { _Pragma("unroll") for (int n = 0; n < 2; ++n) _Pragma("unroll") for (int k = 0; k < 2; ++k) dst[n][k] = *(const PG8_LAS bf16x8*)(lds + PG8_SB(b, h) + boff + n * 2048 + k * 1024); } while (0)
; #define PG8_WAIT_V(n) asm volatile("s_waitcnt vmcnt(" #n ")" ::: "memory")
; #define PG8_WAIT_L(n) asm volatile("s_waitcnt lgkmcnt(" #n ")" ::: "memory")
; #define PG8_BAR __builtin_amdgcn_s_barrier()
; #define PG8_SCHED __builtin_amdgcn_sched_barrier(0)
;     ...
;             PG8_LDB(B0, 1, 0); PG8_LDB(B1, 1, 1); PG8_SCHED; PG8_LDA(At, 1, 0); PG8_STAGE(PG8_SA(0, 1), a2 + hstepA, voffA);
;             PG8_WAIT_V(8); PG8_WAIT_L(0); PG8_BAR; PG8_MMA(0, 0, At, B0); PG8_MMA(0, 1, At, B1); PG8_BAR; PG8_SCHED;
;             PG8_LDA(At, 1, 1); PG8_STAGE(PG8_SB(1, 0), b3, voffB); PG8_STAGE(PG8_SB(1, 1), b3 + hstepB, voffB); PG8_STAGE(PG8_SA(1, 0), a3, voffA);
;             PG8_WAIT_V(8); PG8_WAIT_L(0); PG8_BAR; PG8_MMA(1, 0, At, B0); PG8_MMA(1, 1, At, B1); PG8_BAR; PG8_SCHED;
	s_add_i32 s67, 0, 0x18000
	s_add_i32 s68, 0, 0x1c000
	ds_read_b128 v[146:149], v163 offset:32768
	ds_read_b128 v[150:153], v163 offset:33792
	ds_read_b128 v[154:157], v163 offset:34816
	ds_read_b128 v[158:161], v163 offset:35840
	ds_read_b128 v[186:189], v163 offset:49152
	ds_read_b128 v[190:193], v163 offset:50176
	ds_read_b128 v[194:197], v163 offset:51200
	ds_read_b128 v[198:201], v163 offset:52224
	s_add_u32 s42, s52, 0x160000
	s_addc_u32 s43, s53, 0
	s_mov_b32 m0, s54
	ds_read_b128 v[202:205], v145 offset:32768
	ds_read_b128 v[206:209], v145 offset:33792
	ds_read_b128 v[210:213], v145 offset:34816
	ds_read_b128 v[214:217], v145 offset:35840
	ds_read_b128 v[218:221], v145 offset:36864
	ds_read_b128 v[222:225], v145 offset:37888
	ds_read_b128 v[234:237], v145 offset:38912
	ds_read_b128 v[238:241], v145 offset:39936
	global_load_lds_dwordx4 v132, s[42:43]
	s_mov_b32 m0, s55
	s_nop 0
	global_load_lds_dwordx4 v134, s[42:43]
	s_waitcnt vmcnt(8)
	s_waitcnt lgkmcnt(0)
	s_barrier
	s_setprio 1
	v_mfma_f32_16x16x32_bf16 v[128:131], v[146:149], v[202:205], v[128:131]
	v_mfma_f32_16x16x32_bf16 v[124:127], v[154:157], v[202:205], v[124:127]
	v_mfma_f32_16x16x32_bf16 v[120:123], v[146:149], v[210:213], v[120:123]
	v_mfma_f32_16x16x32_bf16 v[116:119], v[154:157], v[210:213], v[116:119]
	v_mfma_f32_16x16x32_bf16 v[104:107], v[146:149], v[218:221], v[104:107]
	v_mfma_f32_16x16x32_bf16 v[100:103], v[154:157], v[218:221], v[100:103]
	v_mfma_f32_16x16x32_bf16 v[88:91], v[146:149], v[234:237], v[88:91]
	v_mfma_f32_16x16x32_bf16 v[84:87], v[154:157], v[234:237], v[84:87]
	v_mfma_f32_16x16x32_bf16 v[128:131], v[150:153], v[206:209], v[128:131]
	v_mfma_f32_16x16x32_bf16 v[124:127], v[158:161], v[206:209], v[124:127]
	v_mfma_f32_16x16x32_bf16 v[120:123], v[150:153], v[214:217], v[120:123]
	v_mfma_f32_16x16x32_bf16 v[116:119], v[158:161], v[214:217], v[116:119]
	v_mfma_f32_16x16x32_bf16 v[104:107], v[150:153], v[222:225], v[104:107]
	v_mfma_f32_16x16x32_bf16 v[100:103], v[158:161], v[222:225], v[100:103]
	v_mfma_f32_16x16x32_bf16 v[88:91], v[150:153], v[238:241], v[88:91]
	v_mfma_f32_16x16x32_bf16 v[84:87], v[158:161], v[238:241], v[84:87]
	v_mfma_f32_16x16x32_bf16 v[112:115], v[186:189], v[202:205], v[112:115]
	v_mfma_f32_16x16x32_bf16 v[108:111], v[194:197], v[202:205], v[108:111]
	v_mfma_f32_16x16x32_bf16 v[96:99], v[186:189], v[210:213], v[96:99]
	v_mfma_f32_16x16x32_bf16 v[92:95], v[194:197], v[210:213], v[92:95]
	v_mfma_f32_16x16x32_bf16 v[80:83], v[186:189], v[218:221], v[80:83]
	v_mfma_f32_16x16x32_bf16 v[76:79], v[194:197], v[218:221], v[76:79]
	v_mfma_f32_16x16x32_bf16 v[72:75], v[186:189], v[234:237], v[72:75]
	v_mfma_f32_16x16x32_bf16 v[68:71], v[194:197], v[234:237], v[68:71]
	v_mfma_f32_16x16x32_bf16 v[112:115], v[190:193], v[206:209], v[112:115]
	v_mfma_f32_16x16x32_bf16 v[108:111], v[198:201], v[206:209], v[108:111]
	v_mfma_f32_16x16x32_bf16 v[96:99], v[190:193], v[214:217], v[96:99]
	v_mfma_f32_16x16x32_bf16 v[92:95], v[198:201], v[214:217], v[92:95]
	v_mfma_f32_16x16x32_bf16 v[80:83], v[190:193], v[222:225], v[80:83]
	v_mfma_f32_16x16x32_bf16 v[76:79], v[198:201], v[222:225], v[76:79]
	v_mfma_f32_16x16x32_bf16 v[72:75], v[190:193], v[238:241], v[72:75]
	v_mfma_f32_16x16x32_bf16 v[68:71], v[198:201], v[238:241], v[68:71]
	s_setprio 0
	s_barrier
	s_add_i32 s42, s67, s15
	s_mov_b32 m0, s42
	ds_read_b128 v[202:205], v145 offset:49152
	ds_read_b128 v[206:209], v145 offset:50176
	ds_read_b128 v[210:213], v145 offset:51200
	ds_read_b128 v[214:217], v145 offset:52224
	ds_read_b128 v[218:221], v145 offset:53248
	ds_read_b128 v[222:225], v145 offset:54272
	ds_read_b128 v[234:237], v145 offset:55296
	ds_read_b128 v[238:241], v145 offset:56320
	s_add_u32 vcc_lo, s50, 0x80
	s_addc_u32 vcc_hi, s51, 0
	global_load_lds_dwordx4 v34, vcc
	s_add_i32 m0, s42, 0x2000
	s_add_u32 s42, s50, 0x160080
	s_addc_u32 s43, s51, 0
	s_add_i32 s50, s68, s15
	global_load_lds_dwordx4 v136, s[98:99]
	s_mov_b32 m0, s50
	s_nop 0
	global_load_lds_dwordx4 v34, s[42:43]
	s_add_i32 m0, s50, 0x2000
	s_nop 0
	global_load_lds_dwordx4 v136, s[42:43]
	s_mov_b32 m0, s56
	s_add_u32 vcc_lo, s52, 0x80
	s_addc_u32 vcc_hi, s53, 0
	global_load_lds_dwordx4 v132, vcc
	s_mov_b32 m0, s57
	s_nop 0
	global_load_lds_dwordx4 v134, vcc
	s_waitcnt vmcnt(8)
	s_waitcnt lgkmcnt(0)
	s_barrier
	s_setprio 1
	v_mfma_f32_16x16x32_bf16 v[64:67], v[146:149], v[202:205], v[64:67]
	v_mfma_f32_16x16x32_bf16 v[60:63], v[154:157], v[202:205], v[60:63]
	v_mfma_f32_16x16x32_bf16 v[56:59], v[146:149], v[210:213], v[56:59]
	v_mfma_f32_16x16x32_bf16 v[52:55], v[154:157], v[210:213], v[52:55]
	v_mfma_f32_16x16x32_bf16 v[40:43], v[146:149], v[218:221], v[40:43]
	v_mfma_f32_16x16x32_bf16 v[36:39], v[154:157], v[218:221], v[36:39]
	v_mfma_f32_16x16x32_bf16 v[22:25], v[146:149], v[234:237], v[22:25]
	v_mfma_f32_16x16x32_bf16 v[18:21], v[154:157], v[234:237], v[18:21]
	v_mfma_f32_16x16x32_bf16 v[64:67], v[150:153], v[206:209], v[64:67]
	v_mfma_f32_16x16x32_bf16 v[60:63], v[158:161], v[206:209], v[60:63]
	v_mfma_f32_16x16x32_bf16 v[56:59], v[150:153], v[214:217], v[56:59]
	v_mfma_f32_16x16x32_bf16 v[52:55], v[158:161], v[214:217], v[52:55]
	v_mfma_f32_16x16x32_bf16 v[40:43], v[150:153], v[222:225], v[40:43]
	v_mfma_f32_16x16x32_bf16 v[36:39], v[158:161], v[222:225], v[36:39]
	v_mfma_f32_16x16x32_bf16 v[22:25], v[150:153], v[238:241], v[22:25]
	v_mfma_f32_16x16x32_bf16 v[18:21], v[158:161], v[238:241], v[18:21]
	v_mfma_f32_16x16x32_bf16 v[48:51], v[186:189], v[202:205], v[48:51]
	v_mfma_f32_16x16x32_bf16 v[44:47], v[194:197], v[202:205], v[44:47]
	v_mfma_f32_16x16x32_bf16 v[30:33], v[186:189], v[210:213], v[30:33]
	v_mfma_f32_16x16x32_bf16 v[26:29], v[194:197], v[210:213], v[26:29]
	v_mfma_f32_16x16x32_bf16 v[14:17], v[186:189], v[218:221], v[14:17]
	v_mfma_f32_16x16x32_bf16 v[10:13], v[194:197], v[218:221], v[10:13]
	v_mfma_f32_16x16x32_bf16 v[6:9], v[186:189], v[234:237], v[6:9]
	v_mfma_f32_16x16x32_bf16 v[2:5], v[194:197], v[234:237], v[2:5]
	v_mfma_f32_16x16x32_bf16 v[48:51], v[190:193], v[206:209], v[48:51]
	v_mfma_f32_16x16x32_bf16 v[44:47], v[198:201], v[206:209], v[44:47]
	v_mfma_f32_16x16x32_bf16 v[30:33], v[190:193], v[214:217], v[30:33]
	v_mfma_f32_16x16x32_bf16 v[26:29], v[198:201], v[214:217], v[26:29]
	v_mfma_f32_16x16x32_bf16 v[14:17], v[190:193], v[222:225], v[14:17]
	v_mfma_f32_16x16x32_bf16 v[10:13], v[198:201], v[222:225], v[10:13]
	v_mfma_f32_16x16x32_bf16 v[6:9], v[190:193], v[238:241], v[6:9]
	v_mfma_f32_16x16x32_bf16 v[2:5], v[198:201], v[238:241], v[2:5]
	s_setprio 0
	s_barrier
	s_add_i32 s66, s66, 2
	s_add_u32 s64, s64, 0x100
	s_addc_u32 s65, s65, 0
	s_cmpk_gt_u32 s66, 0x55
	s_mov_b64 s[42:43], s[44:45]
	s_cbranch_scc0 .LBB0_694
	s_and_b64 vcc, exec, s[30:31]
	s_cbranch_vccz .LBB0_697
	s_barrier

; #define PG8_STAGE(bufoff, gbase, voff) do { _Pragma("unroll") for (int _i = 0; _i < 2; ++_i) \
;         __builtin_amdgcn_global_load_lds((const unsigned*)((const char*)(gbase) + (voff)[_i]), (PG8_LAS unsigned*)(lds + (bufoff) + ldsw + _i * 8192), 16, 0, 0); } while (0)
; #define PG8_LDA(dst, b, h) do { _Pragma("unroll") for (int m = 0; m < 4; ++m) _Pragma("unroll") for (int k = 0; k < 2; ++k) dst[m][k] = *(const PG8_LAS bf16x8*)(lds + PG8_SA(b, h) + aoff + m * 2048 + k * 1024); } while (0)
; #define PG8_LDB(dst, b, h) do { _Pragma("unroll") for (int n = 0; n < 2; ++n) _Pragma("unroll") for (int k = 0; k < 2; ++k) dst[n][k] = *(const PG8_LAS bf16x8*)(lds + PG8_SB(b, h) + boff + n * 2048 + k * 1024); } while (0)
; #define PG8_WAIT_V(n) asm volatile("s_waitcnt vmcnt(" #n ")" ::: "memory")
; #define PG8_WAIT_L(n) asm volatile("s_waitcnt lgkmcnt(" #n ")" ::: "memory")
; #define PG8_BAR __builtin_amdgcn_s_barrier()
; #define PG8_SCHED __builtin_amdgcn_sched_barrier(0)
;     ...
;         for (int t = 0; t < nt; t += 2) {
;             const bool last = (t == nt - 2);
;             const char* a1 = cA + (size_t)(t + 1) * kstep;
;             const char* a2 = last ? nA : cA + (size_t)(t + 2) * kstep; const char* b2 = last ? nB : cB + (size_t)(t + 2) * kstep;
;             const char* a3 = a2 + kstep; const char* b3 = b2 + kstep;
;             if (last && has_next) S.a_ready(nxt);
;             if constexpr (SP2) {
;             PG8_LDB(B0, 0, 0); PG8_LDB(B1, 0, 1); PG8_SCHED; PG8_LDA(At, 0, 0); PG8_STAGE(PG8_SA(1, 1), a1 + hstepA, voffA);
;             PG8_WAIT_V(8); PG8_WAIT_L(0); PG8_BAR; PG8_MMA(0, 0, At, B0); PG8_MMA(0, 1, At, B1); PG8_BAR; PG8_SCHED;
;             PG8_LDA(At, 0, 1); PG8_STAGE(PG8_SB(0, 0), b2, voffB); PG8_STAGE(PG8_SB(0, 1), b2 + hstepB, voffB); PG8_STAGE(PG8_SA(0, 0), a2, voffA);
;             PG8_WAIT_V(8); PG8_WAIT_L(0); PG8_BAR; PG8_MMA(1, 0, At, B0); PG8_MMA(1, 1, At, B1); PG8_BAR; PG8_SCHED;
.LBB0_726:
	v_add_u32_e32 v250, 0x10000, v209
	s_add_u32 s40, s42, 0x100
	s_addc_u32 s41, s43, 0
	s_add_i32 s64, 0, 0x10000
	s_cmp_eq_u32 s63, 40
	s_cselect_b32 s51, s31, s41
	s_cselect_b32 s50, s30, s40
	s_cselect_b32 s45, s37, s62
	s_cselect_b32 s44, s36, s61
	s_add_i32 s65, 0, 0x14000
	ds_read_b128 v[26:29], v250
	ds_read_b128 v[30:33], v250 offset:1024
	ds_read_b128 v[18:21], v250 offset:2048
	ds_read_b128 v[22:25], v250 offset:3072
	ds_read_b128 v[10:13], v250 offset:16384
	ds_read_b128 v[14:17], v250 offset:17408
	ds_read_b128 v[2:5], v250 offset:18432
	ds_read_b128 v[6:9], v250 offset:19456
	s_add_i32 m0, s21, 0xc000
	ds_read_b128 v[200:203], v211
	ds_read_b128 v[204:207], v211 offset:1024
	ds_read_b128 v[212:215], v211 offset:2048
	ds_read_b128 v[216:219], v211 offset:3072
	ds_read_b128 v[220:223], v211 offset:4096
	ds_read_b128 v[224:227], v211 offset:5120
	ds_read_b128 v[234:237], v211 offset:6144
	ds_read_b128 v[238:241], v211 offset:7168
	global_load_lds_dwordx4 v196, s[42:43]
	s_add_i32 m0, s21, 0xe000
	s_nop 0
	global_load_lds_dwordx4 v198, s[42:43]
	s_waitcnt vmcnt(8)
	s_waitcnt lgkmcnt(0)
	s_barrier
	s_setprio 1
	v_mfma_f32_16x16x128_f8f6f4 v[160:163], v[26:33], v[200:207], v[160:163]
	v_mfma_f32_16x16x128_f8f6f4 v[156:159], v[18:25], v[200:207], v[156:159]
	v_mfma_f32_16x16x128_f8f6f4 v[152:155], v[26:33], v[212:219], v[152:155]
	v_mfma_f32_16x16x128_f8f6f4 v[144:147], v[18:25], v[212:219], v[144:147]
	v_mfma_f32_16x16x128_f8f6f4 v[136:139], v[26:33], v[220:227], v[136:139]
	v_mfma_f32_16x16x128_f8f6f4 v[128:131], v[18:25], v[220:227], v[128:131]
	v_mfma_f32_16x16x128_f8f6f4 v[120:123], v[26:33], v[234:241], v[120:123]
	v_mfma_f32_16x16x128_f8f6f4 v[112:115], v[18:25], v[234:241], v[112:115]
	v_mfma_f32_16x16x128_f8f6f4 v[148:151], v[10:17], v[200:207], v[148:151]
	v_mfma_f32_16x16x128_f8f6f4 v[140:143], v[2:9], v[200:207], v[140:143]
	v_mfma_f32_16x16x128_f8f6f4 v[132:135], v[10:17], v[212:219], v[132:135]
	v_mfma_f32_16x16x128_f8f6f4 v[124:127], v[2:9], v[212:219], v[124:127]
	v_mfma_f32_16x16x128_f8f6f4 v[116:119], v[10:17], v[220:227], v[116:119]
	v_mfma_f32_16x16x128_f8f6f4 v[108:111], v[2:9], v[220:227], v[108:111]
	v_mfma_f32_16x16x128_f8f6f4 v[104:107], v[10:17], v[234:241], v[104:107]
	v_mfma_f32_16x16x128_f8f6f4 v[100:103], v[2:9], v[234:241], v[100:103]
	s_setprio 0
	s_barrier
	s_add_i32 s42, s64, s15
	s_mov_b32 m0, s42
	ds_read_b128 v[212:215], v211 offset:16384
	ds_read_b128 v[216:219], v211 offset:17408
	ds_read_b128 v[220:223], v211 offset:18432
	ds_read_b128 v[224:227], v211 offset:19456
	ds_read_b128 v[234:237], v211 offset:20480
	ds_read_b128 v[238:241], v211 offset:21504
	ds_read_b128 v[242:245], v211 offset:22528
	ds_read_b128 v[246:249], v211 offset:23552
	global_load_lds_dwordx4 v34, s[44:45]
	s_add_i32 m0, s42, 0x2000
	s_add_u32 s42, s44, 0xb0000
	s_addc_u32 s43, s45, 0
	s_add_u32 s98, s44, 0x80
	s_addc_u32 s99, s45, 0
	s_add_i32 s64, s65, s15
	global_load_lds_dwordx4 v190, s[44:45]
	s_mov_b32 m0, s64
	s_nop 0
	global_load_lds_dwordx4 v34, s[42:43]
	s_add_i32 m0, s64, 0x2000
	s_nop 0
	global_load_lds_dwordx4 v190, s[42:43]
	s_mov_b32 m0, s21
	s_nop 0
	global_load_lds_dwordx4 v186, s[50:51]
	s_mov_b32 m0, s34
	s_nop 0
	global_load_lds_dwordx4 v188, s[50:51]
	s_waitcnt vmcnt(8)
	s_waitcnt lgkmcnt(0)
	s_barrier
	s_setprio 1
	v_mfma_f32_16x16x128_f8f6f4 v[96:99], v[26:33], v[212:219], v[96:99]
	v_mfma_f32_16x16x128_f8f6f4 v[92:95], v[18:25], v[212:219], v[92:95]
	v_mfma_f32_16x16x128_f8f6f4 v[88:91], v[26:33], v[220:227], v[88:91]
	v_mfma_f32_16x16x128_f8f6f4 v[80:83], v[18:25], v[220:227], v[80:83]
	v_mfma_f32_16x16x128_f8f6f4 v[72:75], v[26:33], v[234:241], v[72:75]
	v_mfma_f32_16x16x128_f8f6f4 v[64:67], v[18:25], v[234:241], v[64:67]
	v_mfma_f32_16x16x128_f8f6f4 v[56:59], v[26:33], v[242:249], v[56:59]
	v_mfma_f32_16x16x128_f8f6f4 v[48:51], v[18:25], v[242:249], v[48:51]
	v_mfma_f32_16x16x128_f8f6f4 v[84:87], v[10:17], v[212:219], v[84:87]
	v_mfma_f32_16x16x128_f8f6f4 v[76:79], v[2:9], v[212:219], v[76:79]
	v_mfma_f32_16x16x128_f8f6f4 v[68:71], v[10:17], v[220:227], v[68:71]
	v_mfma_f32_16x16x128_f8f6f4 v[60:63], v[2:9], v[220:227], v[60:63]
	v_mfma_f32_16x16x128_f8f6f4 v[52:55], v[10:17], v[234:241], v[52:55]
	v_mfma_f32_16x16x128_f8f6f4 v[44:47], v[2:9], v[234:241], v[44:47]
	v_mfma_f32_16x16x128_f8f6f4 v[40:43], v[10:17], v[242:249], v[40:43]
	v_mfma_f32_16x16x128_f8f6f4 v[36:39], v[2:9], v[242:249], v[36:39]
	s_setprio 0
	s_barrier
; #define PG8_STAGE(bufoff, gbase, voff) do { _Pragma("unroll") for (int _i = 0; _i < 2; ++_i) \
;         __builtin_amdgcn_global_load_lds((const unsigned*)((const char*)(gbase) + (voff)[_i]), (PG8_LAS unsigned*)(lds + (bufoff) + ldsw + _i * 8192), 16, 0, 0); } while (0)
; #define PG8_LDA(dst, b, h) do { _Pragma("unroll") for (int m = 0; m < 4; ++m) _Pragma("unroll") for (int k = 0; k < 2; ++k) dst[m][k] = *(const PG8_LAS bf16x8*)(lds + PG8_SA(b, h) + aoff + m * 2048 + k * 1024); } while (0)
; #define PG8_LDB(dst, b, h) do { _Pragma("unroll") for (int n = 0; n < 2; ++n) _Pragma("unroll") for (int k = 0; k < 2; ++k) dst[n][k] = *(const PG8_LAS bf16x8*)(lds + PG8_SB(b, h) + boff + n * 2048 + k * 1024); } while (0)
; #define PG8_WAIT_V(n) asm volatile("s_waitcnt vmcnt(" #n ")" ::: "memory")
; #define PG8_WAIT_L(n) asm volatile("s_waitcnt lgkmcnt(" #n ")" ::: "memory")
; #define PG8_BAR __builtin_amdgcn_s_barrier()
; #define PG8_SCHED __builtin_amdgcn_sched_barrier(0)
;     ...
;             PG8_LDB(B0, 1, 0); PG8_LDB(B1, 1, 1); PG8_SCHED; PG8_LDA(At, 1, 0); PG8_STAGE(PG8_SA(0, 1), a2 + hstepA, voffA);
;             PG8_WAIT_V(8); PG8_WAIT_L(0); PG8_BAR; PG8_MMA(0, 0, At, B0); PG8_MMA(0, 1, At, B1); PG8_BAR; PG8_SCHED;
;             PG8_LDA(At, 1, 1); PG8_STAGE(PG8_SB(1, 0), b3, voffB); PG8_STAGE(PG8_SB(1, 1), b3 + hstepB, voffB); PG8_STAGE(PG8_SA(1, 0), a3, voffA);
;             PG8_WAIT_V(8); PG8_WAIT_L(0); PG8_BAR; PG8_MMA(1, 0, At, B0); PG8_MMA(1, 1, At, B1); PG8_BAR; PG8_SCHED;
	s_add_i32 s64, 0, 0x18000
	s_add_i32 s65, 0, 0x1c000
	ds_read_b128 v[2:5], v250 offset:32768
	ds_read_b128 v[6:9], v250 offset:33792
	ds_read_b128 v[10:13], v250 offset:34816
	ds_read_b128 v[14:17], v250 offset:35840
	ds_read_b128 v[18:21], v250 offset:49152
	ds_read_b128 v[22:25], v250 offset:50176
	ds_read_b128 v[26:29], v250 offset:51200
	ds_read_b128 v[30:33], v250 offset:52224
	s_add_u32 s42, s50, 0xb0000
	s_addc_u32 s43, s51, 0
	s_mov_b32 m0, s35
	ds_read_b128 v[212:215], v211 offset:32768
	ds_read_b128 v[216:219], v211 offset:33792
	ds_read_b128 v[220:223], v211 offset:34816
	ds_read_b128 v[224:227], v211 offset:35840
	ds_read_b128 v[234:237], v211 offset:36864
	ds_read_b128 v[238:241], v211 offset:37888
	ds_read_b128 v[242:245], v211 offset:38912
	ds_read_b128 v[246:249], v211 offset:39936
	global_load_lds_dwordx4 v186, s[42:43]
	s_mov_b32 m0, s52
	s_nop 0
	global_load_lds_dwordx4 v188, s[42:43]
	s_waitcnt vmcnt(8)
	s_waitcnt lgkmcnt(0)
	s_barrier
	s_setprio 1
	v_mfma_f32_16x16x128_f8f6f4 v[160:163], v[2:9], v[212:219], v[160:163]
	v_mfma_f32_16x16x128_f8f6f4 v[156:159], v[10:17], v[212:219], v[156:159]
	v_mfma_f32_16x16x128_f8f6f4 v[152:155], v[2:9], v[220:227], v[152:155]
	v_mfma_f32_16x16x128_f8f6f4 v[144:147], v[10:17], v[220:227], v[144:147]
	v_mfma_f32_16x16x128_f8f6f4 v[136:139], v[2:9], v[234:241], v[136:139]
	v_mfma_f32_16x16x128_f8f6f4 v[128:131], v[10:17], v[234:241], v[128:131]
	v_mfma_f32_16x16x128_f8f6f4 v[120:123], v[2:9], v[242:249], v[120:123]
	v_mfma_f32_16x16x128_f8f6f4 v[112:115], v[10:17], v[242:249], v[112:115]
	v_mfma_f32_16x16x128_f8f6f4 v[148:151], v[18:25], v[212:219], v[148:151]
	v_mfma_f32_16x16x128_f8f6f4 v[140:143], v[26:33], v[212:219], v[140:143]
	v_mfma_f32_16x16x128_f8f6f4 v[132:135], v[18:25], v[220:227], v[132:135]
	v_mfma_f32_16x16x128_f8f6f4 v[124:127], v[26:33], v[220:227], v[124:127]
	v_mfma_f32_16x16x128_f8f6f4 v[116:119], v[18:25], v[234:241], v[116:119]
	v_mfma_f32_16x16x128_f8f6f4 v[108:111], v[26:33], v[234:241], v[108:111]
	v_mfma_f32_16x16x128_f8f6f4 v[104:107], v[18:25], v[242:249], v[104:107]
	v_mfma_f32_16x16x128_f8f6f4 v[100:103], v[26:33], v[242:249], v[100:103]
	s_setprio 0
	s_barrier
	s_add_i32 s42, s64, s15
	s_mov_b32 m0, s42
	ds_read_b128 v[212:215], v211 offset:49152
	ds_read_b128 v[216:219], v211 offset:50176
	ds_read_b128 v[220:223], v211 offset:51200
	ds_read_b128 v[224:227], v211 offset:52224
	ds_read_b128 v[234:237], v211 offset:53248
	ds_read_b128 v[238:241], v211 offset:54272
	ds_read_b128 v[242:245], v211 offset:55296
	ds_read_b128 v[246:249], v211 offset:56320
	s_add_u32 vcc_lo, s44, 0x80
	s_addc_u32 vcc_hi, s45, 0
	global_load_lds_dwordx4 v34, vcc
	s_add_i32 m0, s42, 0x2000
	s_add_u32 s42, s44, 0xb0080
	s_addc_u32 s43, s45, 0
	s_add_i32 s44, s65, s15
	global_load_lds_dwordx4 v190, s[98:99]
	s_mov_b32 m0, s44
	s_nop 0
	global_load_lds_dwordx4 v34, s[42:43]
	s_add_i32 m0, s44, 0x2000
	s_nop 0
	global_load_lds_dwordx4 v190, s[42:43]
	s_mov_b32 m0, s53
	s_add_u32 vcc_lo, s50, 0x80
	s_addc_u32 vcc_hi, s51, 0
	global_load_lds_dwordx4 v186, vcc
	s_mov_b32 m0, s54
	s_nop 0
	global_load_lds_dwordx4 v188, vcc
	s_waitcnt vmcnt(8)
	s_waitcnt lgkmcnt(0)
	s_barrier
	s_setprio 1
	v_mfma_f32_16x16x128_f8f6f4 v[96:99], v[2:9], v[212:219], v[96:99]
	v_mfma_f32_16x16x128_f8f6f4 v[92:95], v[10:17], v[212:219], v[92:95]
	v_mfma_f32_16x16x128_f8f6f4 v[88:91], v[2:9], v[220:227], v[88:91]
	v_mfma_f32_16x16x128_f8f6f4 v[80:83], v[10:17], v[220:227], v[80:83]
	v_mfma_f32_16x16x128_f8f6f4 v[72:75], v[2:9], v[234:241], v[72:75]
	v_mfma_f32_16x16x128_f8f6f4 v[64:67], v[10:17], v[234:241], v[64:67]
	v_mfma_f32_16x16x128_f8f6f4 v[56:59], v[2:9], v[242:249], v[56:59]
	v_mfma_f32_16x16x128_f8f6f4 v[48:51], v[10:17], v[242:249], v[48:51]
	v_mfma_f32_16x16x128_f8f6f4 v[84:87], v[18:25], v[212:219], v[84:87]
	v_mfma_f32_16x16x128_f8f6f4 v[76:79], v[26:33], v[212:219], v[76:79]
	v_mfma_f32_16x16x128_f8f6f4 v[68:71], v[18:25], v[220:227], v[68:71]
	v_mfma_f32_16x16x128_f8f6f4 v[60:63], v[26:33], v[220:227], v[60:63]
	v_mfma_f32_16x16x128_f8f6f4 v[52:55], v[18:25], v[234:241], v[52:55]
	v_mfma_f32_16x16x128_f8f6f4 v[44:47], v[26:33], v[234:241], v[44:47]
	v_mfma_f32_16x16x128_f8f6f4 v[40:43], v[18:25], v[242:249], v[40:43]
	v_mfma_f32_16x16x128_f8f6f4 v[36:39], v[26:33], v[242:249], v[36:39]
	s_setprio 0
	s_barrier
	s_add_i32 s63, s63, 2
	s_add_u32 s61, s61, 0x100
	s_addc_u32 s62, s62, 0
	s_cmp_gt_u32 s63, 41
	s_mov_b64 s[42:43], s[40:41]
	s_cbranch_scc0 .LBB0_726
	s_and_b64 vcc, exec, s[28:29]
	s_cbranch_vccz .LBB0_729
	s_barrier

; #define PG8_STAGE(bufoff, gbase, voff) do { _Pragma("unroll") for (int _i = 0; _i < 2; ++_i) \
;         __builtin_amdgcn_global_load_lds((const unsigned*)((const char*)(gbase) + (voff)[_i]), (PG8_LAS unsigned*)(lds + (bufoff) + ldsw + _i * 8192), 16, 0, 0); } while (0)
; #define PG8_LDA(dst, b, h) do { _Pragma("unroll") for (int m = 0; m < 4; ++m) _Pragma("unroll") for (int k = 0; k < 2; ++k) dst[m][k] = *(const PG8_LAS bf16x8*)(lds + PG8_SA(b, h) + aoff + m * 2048 + k * 1024); } while (0)
; #define PG8_LDB(dst, b, h) do { _Pragma("unroll") for (int n = 0; n < 2; ++n) _Pragma("unroll") for (int k = 0; k < 2; ++k) dst[n][k] = *(const PG8_LAS bf16x8*)(lds + PG8_SB(b, h) + boff + n * 2048 + k * 1024); } while (0)
; #define PG8_WAIT_V(n) asm volatile("s_waitcnt vmcnt(" #n ")" ::: "memory")
; #define PG8_WAIT_L(n) asm volatile("s_waitcnt lgkmcnt(" #n ")" ::: "memory")
; #define PG8_BAR __builtin_amdgcn_s_barrier()
; #define PG8_SCHED __builtin_amdgcn_sched_barrier(0)
;     ...
;         for (int t = 0; t < nt; t += 2) {
;             const bool last = (t == nt - 2);
;             const char* a1 = cA + (size_t)(t + 1) * kstep;
;             const char* a2 = last ? nA : cA + (size_t)(t + 2) * kstep; const char* b2 = last ? nB : cB + (size_t)(t + 2) * kstep;
;             const char* a3 = a2 + kstep; const char* b3 = b2 + kstep;
;             if (last && has_next) S.a_ready(nxt);
;             if constexpr (SP2) {
;             PG8_LDB(B0, 0, 0); PG8_LDB(B1, 0, 1); PG8_SCHED; PG8_LDA(At, 0, 0); PG8_STAGE(PG8_SA(1, 1), a1 + hstepA, voffA);
;             PG8_WAIT_V(8); PG8_WAIT_L(0); PG8_BAR; PG8_MMA(0, 0, At, B0); PG8_MMA(0, 1, At, B1); PG8_BAR; PG8_SCHED;
;             PG8_LDA(At, 0, 1); PG8_STAGE(PG8_SB(0, 0), b2, voffB); PG8_STAGE(PG8_SB(0, 1), b2 + hstepB, voffB); PG8_STAGE(PG8_SA(0, 0), a2, voffA);
;             PG8_WAIT_V(8); PG8_WAIT_L(0); PG8_BAR; PG8_MMA(1, 0, At, B0); PG8_MMA(1, 1, At, B1); PG8_BAR; PG8_SCHED;
.LBB0_1153:
	v_add_u32_e32 v162, 0x10000, v155
	s_add_u32 s34, s26, 0xfff80080
	s_addc_u32 s35, s27, -1
	s_add_i32 s37, 0, 0x10000
	s_cmp_eq_u32 s19, 28
	s_cselect_b32 s57, s6, s35
	s_cselect_b32 s56, s10, s34
	s_cselect_b32 s41, s11, s15
	s_cselect_b32 s40, s12, s13
	s_add_i32 s49, 0, 0x14000
	ds_read_b128 v[132:135], v162
	ds_read_b128 v[136:139], v162 offset:1024
	s_waitcnt vmcnt(0)
	ds_read_b128 v[158:161], v162 offset:2048
	ds_read_b128 v[186:189], v162 offset:3072
	ds_read_b128 v[190:193], v162 offset:16384
	ds_read_b128 v[194:197], v162 offset:17408
	ds_read_b128 v[198:201], v162 offset:18432
	ds_read_b128 v[202:205], v162 offset:19456
	s_add_i32 m0, s8, 0xc000
	ds_read_b128 v[206:209], v157
	ds_read_b128 v[210:213], v157 offset:1024
	ds_read_b128 v[214:217], v157 offset:2048
	ds_read_b128 v[218:221], v157 offset:3072
	ds_read_b128 v[222:225], v157 offset:4096
	ds_read_b128 v[234:237], v157 offset:5120
	ds_read_b128 v[238:241], v157 offset:6144
	ds_read_b128 v[242:245], v157 offset:7168
	global_load_lds_dwordx4 v150, s[26:27]
	s_add_i32 m0, s8, 0xe000
	s_nop 0
	global_load_lds_dwordx4 v152, s[26:27]
	s_waitcnt vmcnt(8)
	s_waitcnt lgkmcnt(0)
	s_barrier
	s_setprio 1
	v_mfma_f32_16x16x32_bf16 v[128:131], v[132:135], v[206:209], v[128:131]
	v_mfma_f32_16x16x32_bf16 v[124:127], v[158:161], v[206:209], v[124:127]
	v_mfma_f32_16x16x32_bf16 v[112:115], v[132:135], v[214:217], v[112:115]
	v_mfma_f32_16x16x32_bf16 v[108:111], v[158:161], v[214:217], v[108:111]
	v_mfma_f32_16x16x32_bf16 v[96:99], v[132:135], v[222:225], v[96:99]
	v_mfma_f32_16x16x32_bf16 v[92:95], v[158:161], v[222:225], v[92:95]
	v_mfma_f32_16x16x32_bf16 v[80:83], v[132:135], v[238:241], v[80:83]
	v_mfma_f32_16x16x32_bf16 v[76:79], v[158:161], v[238:241], v[76:79]
	v_mfma_f32_16x16x32_bf16 v[128:131], v[136:139], v[210:213], v[128:131]
	v_mfma_f32_16x16x32_bf16 v[124:127], v[186:189], v[210:213], v[124:127]
	v_mfma_f32_16x16x32_bf16 v[112:115], v[136:139], v[218:221], v[112:115]
	v_mfma_f32_16x16x32_bf16 v[108:111], v[186:189], v[218:221], v[108:111]
	v_mfma_f32_16x16x32_bf16 v[96:99], v[136:139], v[234:237], v[96:99]
	v_mfma_f32_16x16x32_bf16 v[92:95], v[186:189], v[234:237], v[92:95]
	v_mfma_f32_16x16x32_bf16 v[80:83], v[136:139], v[242:245], v[80:83]
	v_mfma_f32_16x16x32_bf16 v[76:79], v[186:189], v[242:245], v[76:79]
	v_mfma_f32_16x16x32_bf16 v[120:123], v[190:193], v[206:209], v[120:123]
	v_mfma_f32_16x16x32_bf16 v[116:119], v[198:201], v[206:209], v[116:119]
	v_mfma_f32_16x16x32_bf16 v[104:107], v[190:193], v[214:217], v[104:107]
	v_mfma_f32_16x16x32_bf16 v[100:103], v[198:201], v[214:217], v[100:103]
	v_mfma_f32_16x16x32_bf16 v[88:91], v[190:193], v[222:225], v[88:91]
	v_mfma_f32_16x16x32_bf16 v[84:87], v[198:201], v[222:225], v[84:87]
	v_mfma_f32_16x16x32_bf16 v[72:75], v[190:193], v[238:241], v[72:75]
	v_mfma_f32_16x16x32_bf16 v[68:71], v[198:201], v[238:241], v[68:71]
	v_mfma_f32_16x16x32_bf16 v[120:123], v[194:197], v[210:213], v[120:123]
	v_mfma_f32_16x16x32_bf16 v[116:119], v[202:205], v[210:213], v[116:119]
	v_mfma_f32_16x16x32_bf16 v[104:107], v[194:197], v[218:221], v[104:107]
	v_mfma_f32_16x16x32_bf16 v[100:103], v[202:205], v[218:221], v[100:103]
	v_mfma_f32_16x16x32_bf16 v[88:91], v[194:197], v[234:237], v[88:91]
	v_mfma_f32_16x16x32_bf16 v[84:87], v[202:205], v[234:237], v[84:87]
	v_mfma_f32_16x16x32_bf16 v[72:75], v[194:197], v[242:245], v[72:75]
	v_mfma_f32_16x16x32_bf16 v[68:71], v[202:205], v[242:245], v[68:71]
	s_setprio 0
	s_barrier
	s_add_i32 s34, s37, s7
	s_mov_b32 m0, s34
	ds_read_b128 v[206:209], v157 offset:16384
	ds_read_b128 v[210:213], v157 offset:17408
	ds_read_b128 v[214:217], v157 offset:18432
	ds_read_b128 v[218:221], v157 offset:19456
	ds_read_b128 v[222:225], v157 offset:20480
	ds_read_b128 v[234:237], v157 offset:21504
	ds_read_b128 v[238:241], v157 offset:22528
	ds_read_b128 v[242:245], v157 offset:23552
	global_load_lds_dwordx4 v142, s[40:41]
	s_add_i32 m0, s34, 0x2000
	s_add_u32 s34, s40, 0x80000
	s_addc_u32 s35, s41, 0
	s_add_i32 s37, s49, s7
	global_load_lds_dwordx4 v146, s[40:41]
	s_mov_b32 m0, s37
	s_nop 0
	global_load_lds_dwordx4 v142, s[34:35]
	s_add_i32 m0, s37, 0x2000
	s_nop 0
	global_load_lds_dwordx4 v146, s[34:35]
	s_mov_b32 m0, s8
	s_nop 0
	global_load_lds_dwordx4 v140, s[56:57]
	s_mov_b32 m0, s9
	s_nop 0
	global_load_lds_dwordx4 v144, s[56:57]
	s_waitcnt vmcnt(8)
	s_waitcnt lgkmcnt(0)
	s_barrier
	s_setprio 1
	v_mfma_f32_16x16x32_bf16 v[64:67], v[132:135], v[206:209], v[64:67]
	v_mfma_f32_16x16x32_bf16 v[60:63], v[158:161], v[206:209], v[60:63]
	v_mfma_f32_16x16x32_bf16 v[48:51], v[132:135], v[214:217], v[48:51]
	v_mfma_f32_16x16x32_bf16 v[44:47], v[158:161], v[214:217], v[44:47]
	v_mfma_f32_16x16x32_bf16 v[30:33], v[132:135], v[222:225], v[30:33]
	v_mfma_f32_16x16x32_bf16 v[26:29], v[158:161], v[222:225], v[26:29]
	v_mfma_f32_16x16x32_bf16 v[14:17], v[132:135], v[238:241], v[14:17]
	v_mfma_f32_16x16x32_bf16 v[10:13], v[158:161], v[238:241], v[10:13]
	v_mfma_f32_16x16x32_bf16 v[64:67], v[136:139], v[210:213], v[64:67]
	v_mfma_f32_16x16x32_bf16 v[60:63], v[186:189], v[210:213], v[60:63]
	v_mfma_f32_16x16x32_bf16 v[48:51], v[136:139], v[218:221], v[48:51]
	v_mfma_f32_16x16x32_bf16 v[44:47], v[186:189], v[218:221], v[44:47]
	v_mfma_f32_16x16x32_bf16 v[30:33], v[136:139], v[234:237], v[30:33]
	v_mfma_f32_16x16x32_bf16 v[26:29], v[186:189], v[234:237], v[26:29]
	v_mfma_f32_16x16x32_bf16 v[14:17], v[136:139], v[242:245], v[14:17]
	v_mfma_f32_16x16x32_bf16 v[10:13], v[186:189], v[242:245], v[10:13]
	v_mfma_f32_16x16x32_bf16 v[56:59], v[190:193], v[206:209], v[56:59]
	v_mfma_f32_16x16x32_bf16 v[52:55], v[198:201], v[206:209], v[52:55]
	v_mfma_f32_16x16x32_bf16 v[40:43], v[190:193], v[214:217], v[40:43]
	v_mfma_f32_16x16x32_bf16 v[36:39], v[198:201], v[214:217], v[36:39]
	v_mfma_f32_16x16x32_bf16 v[22:25], v[190:193], v[222:225], v[22:25]
	v_mfma_f32_16x16x32_bf16 v[18:21], v[198:201], v[222:225], v[18:21]
	v_mfma_f32_16x16x32_bf16 v[6:9], v[190:193], v[238:241], v[6:9]
	v_mfma_f32_16x16x32_bf16 v[2:5], v[198:201], v[238:241], v[2:5]
	v_mfma_f32_16x16x32_bf16 v[56:59], v[194:197], v[210:213], v[56:59]
	v_mfma_f32_16x16x32_bf16 v[52:55], v[202:205], v[210:213], v[52:55]
	v_mfma_f32_16x16x32_bf16 v[40:43], v[194:197], v[218:221], v[40:43]
	v_mfma_f32_16x16x32_bf16 v[36:39], v[202:205], v[218:221], v[36:39]
	v_mfma_f32_16x16x32_bf16 v[22:25], v[194:197], v[234:237], v[22:25]
	v_mfma_f32_16x16x32_bf16 v[18:21], v[202:205], v[234:237], v[18:21]
	v_mfma_f32_16x16x32_bf16 v[6:9], v[194:197], v[242:245], v[6:9]
	v_mfma_f32_16x16x32_bf16 v[2:5], v[202:205], v[242:245], v[2:5]
	s_setprio 0
	s_barrier
; #define PG8_STAGE(bufoff, gbase, voff) do { _Pragma("unroll") for (int _i = 0; _i < 2; ++_i) \
;         __builtin_amdgcn_global_load_lds((const unsigned*)((const char*)(gbase) + (voff)[_i]), (PG8_LAS unsigned*)(lds + (bufoff) + ldsw + _i * 8192), 16, 0, 0); } while (0)
; #define PG8_LDA(dst, b, h) do { _Pragma("unroll") for (int m = 0; m < 4; ++m) _Pragma("unroll") for (int k = 0; k < 2; ++k) dst[m][k] = *(const PG8_LAS bf16x8*)(lds + PG8_SA(b, h) + aoff + m * 2048 + k * 1024); } while (0)
; #define PG8_LDB(dst, b, h) do { _Pragma("unroll") for (int n = 0; n < 2; ++n) _Pragma("unroll") for (int k = 0; k < 2; ++k) dst[n][k] = *(const PG8_LAS bf16x8*)(lds + PG8_SB(b, h) + boff + n * 2048 + k * 1024); } while (0)
; #define PG8_WAIT_V(n) asm volatile("s_waitcnt vmcnt(" #n ")" ::: "memory")
; #define PG8_WAIT_L(n) asm volatile("s_waitcnt lgkmcnt(" #n ")" ::: "memory")
; #define PG8_BAR __builtin_amdgcn_s_barrier()
; #define PG8_SCHED __builtin_amdgcn_sched_barrier(0)
;     ...
;         for (int t = 0; t < nt; t += 2) {
;             const bool last = (t == nt - 2);
;             const char* a1 = cA + (size_t)(t + 1) * kstep;
;             const char* a2 = last ? nA : cA + (size_t)(t + 2) * kstep; const char* b2 = last ? nB : cB + (size_t)(t + 2) * kstep;
;     ...
;             PG8_LDB(B0, 1, 0); PG8_LDB(B1, 1, 1); PG8_SCHED; PG8_LDA(At, 1, 0); PG8_STAGE(PG8_SA(0, 1), a2 + hstepA, voffA);
;             PG8_WAIT_V(8); PG8_WAIT_L(0); PG8_BAR; PG8_MMA(0, 0, At, B0); PG8_MMA(0, 1, At, B1); PG8_BAR; PG8_SCHED;
;             PG8_LDA(At, 1, 1); PG8_STAGE(PG8_SB(1, 0), b3, voffB); PG8_STAGE(PG8_SB(1, 1), b3 + hstepB, voffB); PG8_STAGE(PG8_SA(1, 0), a3, voffA);
;             PG8_WAIT_V(8); PG8_WAIT_L(0); PG8_BAR; PG8_MMA(1, 0, At, B0); PG8_MMA(1, 1, At, B1); PG8_BAR; PG8_SCHED;
	s_add_i32 s37, 0, 0x18000
	s_add_i32 s49, 0, 0x1c000
	ds_read_b128 v[132:135], v162 offset:32768
	ds_read_b128 v[136:139], v162 offset:33792
	ds_read_b128 v[158:161], v162 offset:34816
	ds_read_b128 v[186:189], v162 offset:35840
	ds_read_b128 v[190:193], v162 offset:49152
	ds_read_b128 v[194:197], v162 offset:50176
	ds_read_b128 v[198:201], v162 offset:51200
	ds_read_b128 v[202:205], v162 offset:52224
	s_add_u32 s34, s56, 0x80000
	s_addc_u32 s35, s57, 0
	s_mov_b32 m0, s58
	ds_read_b128 v[206:209], v157 offset:32768
	ds_read_b128 v[210:213], v157 offset:33792
	ds_read_b128 v[214:217], v157 offset:34816
	ds_read_b128 v[218:221], v157 offset:35840
	ds_read_b128 v[222:225], v157 offset:36864
	ds_read_b128 v[234:237], v157 offset:37888
	ds_read_b128 v[238:241], v157 offset:38912
	ds_read_b128 v[242:245], v157 offset:39936
	global_load_lds_dwordx4 v140, s[34:35]
	s_mov_b32 m0, s59
	s_nop 0
	global_load_lds_dwordx4 v144, s[34:35]
	s_waitcnt vmcnt(8)
	s_waitcnt lgkmcnt(0)
	s_barrier
	s_setprio 1
	v_mfma_f32_16x16x32_bf16 v[128:131], v[132:135], v[206:209], v[128:131]
	v_mfma_f32_16x16x32_bf16 v[124:127], v[158:161], v[206:209], v[124:127]
	v_mfma_f32_16x16x32_bf16 v[112:115], v[132:135], v[214:217], v[112:115]
	v_mfma_f32_16x16x32_bf16 v[108:111], v[158:161], v[214:217], v[108:111]
	v_mfma_f32_16x16x32_bf16 v[96:99], v[132:135], v[222:225], v[96:99]
	v_mfma_f32_16x16x32_bf16 v[92:95], v[158:161], v[222:225], v[92:95]
	v_mfma_f32_16x16x32_bf16 v[80:83], v[132:135], v[238:241], v[80:83]
	v_mfma_f32_16x16x32_bf16 v[76:79], v[158:161], v[238:241], v[76:79]
	v_mfma_f32_16x16x32_bf16 v[128:131], v[136:139], v[210:213], v[128:131]
	v_mfma_f32_16x16x32_bf16 v[124:127], v[186:189], v[210:213], v[124:127]
	v_mfma_f32_16x16x32_bf16 v[112:115], v[136:139], v[218:221], v[112:115]
	v_mfma_f32_16x16x32_bf16 v[108:111], v[186:189], v[218:221], v[108:111]
	v_mfma_f32_16x16x32_bf16 v[96:99], v[136:139], v[234:237], v[96:99]
	v_mfma_f32_16x16x32_bf16 v[92:95], v[186:189], v[234:237], v[92:95]
	v_mfma_f32_16x16x32_bf16 v[80:83], v[136:139], v[242:245], v[80:83]
	v_mfma_f32_16x16x32_bf16 v[76:79], v[186:189], v[242:245], v[76:79]
	v_mfma_f32_16x16x32_bf16 v[120:123], v[190:193], v[206:209], v[120:123]
	v_mfma_f32_16x16x32_bf16 v[116:119], v[198:201], v[206:209], v[116:119]
	v_mfma_f32_16x16x32_bf16 v[104:107], v[190:193], v[214:217], v[104:107]
	v_mfma_f32_16x16x32_bf16 v[100:103], v[198:201], v[214:217], v[100:103]
	v_mfma_f32_16x16x32_bf16 v[88:91], v[190:193], v[222:225], v[88:91]
	v_mfma_f32_16x16x32_bf16 v[84:87], v[198:201], v[222:225], v[84:87]
	v_mfma_f32_16x16x32_bf16 v[72:75], v[190:193], v[238:241], v[72:75]
	v_mfma_f32_16x16x32_bf16 v[68:71], v[198:201], v[238:241], v[68:71]
	v_mfma_f32_16x16x32_bf16 v[120:123], v[194:197], v[210:213], v[120:123]
	v_mfma_f32_16x16x32_bf16 v[116:119], v[202:205], v[210:213], v[116:119]
	v_mfma_f32_16x16x32_bf16 v[104:107], v[194:197], v[218:221], v[104:107]
	v_mfma_f32_16x16x32_bf16 v[100:103], v[202:205], v[218:221], v[100:103]
	v_mfma_f32_16x16x32_bf16 v[88:91], v[194:197], v[234:237], v[88:91]
	v_mfma_f32_16x16x32_bf16 v[84:87], v[202:205], v[234:237], v[84:87]
	v_mfma_f32_16x16x32_bf16 v[72:75], v[194:197], v[242:245], v[72:75]
	v_mfma_f32_16x16x32_bf16 v[68:71], v[202:205], v[242:245], v[68:71]
	s_setprio 0
	s_barrier
	s_add_i32 s34, s37, s7
	s_mov_b32 m0, s34
	ds_read_b128 v[206:209], v157 offset:49152
	ds_read_b128 v[210:213], v157 offset:50176
	ds_read_b128 v[214:217], v157 offset:51200
	ds_read_b128 v[218:221], v157 offset:52224
	ds_read_b128 v[222:225], v157 offset:53248
	ds_read_b128 v[234:237], v157 offset:54272
	ds_read_b128 v[238:241], v157 offset:55296
	ds_read_b128 v[242:245], v157 offset:56320
	s_add_u32 vcc_lo, s40, 0x80
	s_addc_u32 vcc_hi, s41, 0
	global_load_lds_dwordx4 v142, vcc
	s_add_i32 m0, s34, 0x2000
	s_add_u32 s34, s40, 0x80080
	s_addc_u32 s35, s41, 0
	s_add_i32 s37, s49, s7
	global_load_lds_dwordx4 v146, vcc
	s_mov_b32 m0, s37
	s_nop 0
	global_load_lds_dwordx4 v142, s[34:35]
	s_add_i32 m0, s37, 0x2000
	s_nop 0
	global_load_lds_dwordx4 v146, s[34:35]
	s_mov_b32 m0, s66
	s_add_u32 vcc_lo, s56, 0x80
	s_addc_u32 vcc_hi, s57, 0
	global_load_lds_dwordx4 v140, vcc
	s_mov_b32 m0, s67
	s_nop 0
	global_load_lds_dwordx4 v144, vcc
	s_waitcnt vmcnt(8)
	s_waitcnt lgkmcnt(0)
	s_barrier
	s_setprio 1
	v_mfma_f32_16x16x32_bf16 v[64:67], v[132:135], v[206:209], v[64:67]
	v_mfma_f32_16x16x32_bf16 v[60:63], v[158:161], v[206:209], v[60:63]
	v_mfma_f32_16x16x32_bf16 v[48:51], v[132:135], v[214:217], v[48:51]
	v_mfma_f32_16x16x32_bf16 v[44:47], v[158:161], v[214:217], v[44:47]
	v_mfma_f32_16x16x32_bf16 v[30:33], v[132:135], v[222:225], v[30:33]
	v_mfma_f32_16x16x32_bf16 v[26:29], v[158:161], v[222:225], v[26:29]
	v_mfma_f32_16x16x32_bf16 v[14:17], v[132:135], v[238:241], v[14:17]
	v_mfma_f32_16x16x32_bf16 v[10:13], v[158:161], v[238:241], v[10:13]
	v_mfma_f32_16x16x32_bf16 v[64:67], v[136:139], v[210:213], v[64:67]
	v_mfma_f32_16x16x32_bf16 v[60:63], v[186:189], v[210:213], v[60:63]
	v_mfma_f32_16x16x32_bf16 v[48:51], v[136:139], v[218:221], v[48:51]
	v_mfma_f32_16x16x32_bf16 v[44:47], v[186:189], v[218:221], v[44:47]
	v_mfma_f32_16x16x32_bf16 v[30:33], v[136:139], v[234:237], v[30:33]
	v_mfma_f32_16x16x32_bf16 v[26:29], v[186:189], v[234:237], v[26:29]
	v_mfma_f32_16x16x32_bf16 v[14:17], v[136:139], v[242:245], v[14:17]
	v_mfma_f32_16x16x32_bf16 v[10:13], v[186:189], v[242:245], v[10:13]
	v_mfma_f32_16x16x32_bf16 v[56:59], v[190:193], v[206:209], v[56:59]
	v_mfma_f32_16x16x32_bf16 v[52:55], v[198:201], v[206:209], v[52:55]
	v_mfma_f32_16x16x32_bf16 v[40:43], v[190:193], v[214:217], v[40:43]
	v_mfma_f32_16x16x32_bf16 v[36:39], v[198:201], v[214:217], v[36:39]
	v_mfma_f32_16x16x32_bf16 v[22:25], v[190:193], v[222:225], v[22:25]
	v_mfma_f32_16x16x32_bf16 v[18:21], v[198:201], v[222:225], v[18:21]
	v_mfma_f32_16x16x32_bf16 v[6:9], v[190:193], v[238:241], v[6:9]
	v_mfma_f32_16x16x32_bf16 v[2:5], v[198:201], v[238:241], v[2:5]
	v_mfma_f32_16x16x32_bf16 v[56:59], v[194:197], v[210:213], v[56:59]
	v_mfma_f32_16x16x32_bf16 v[52:55], v[202:205], v[210:213], v[52:55]
	v_mfma_f32_16x16x32_bf16 v[40:43], v[194:197], v[218:221], v[40:43]
	v_mfma_f32_16x16x32_bf16 v[36:39], v[202:205], v[218:221], v[36:39]
	v_mfma_f32_16x16x32_bf16 v[22:25], v[194:197], v[234:237], v[22:25]
	v_mfma_f32_16x16x32_bf16 v[18:21], v[202:205], v[234:237], v[18:21]
	v_mfma_f32_16x16x32_bf16 v[6:9], v[194:197], v[242:245], v[6:9]
	v_mfma_f32_16x16x32_bf16 v[2:5], v[202:205], v[242:245], v[2:5]
	s_setprio 0
	s_barrier
	s_add_i32 s19, s19, 2
	s_add_u32 s26, s26, 0x100
	s_addc_u32 s27, s27, 0
	s_add_u32 s13, s13, 0x100
	s_addc_u32 s15, s15, 0
	s_cmp_gt_u32 s19, 29
	s_cbranch_scc0 .LBB0_1153
	s_and_b64 vcc, exec, s[46:47]
	s_cbranch_vccz .LBB0_1156
	s_barrier

; #define PG8_STAGE(bufoff, gbase, voff) do { _Pragma("unroll") for (int _i = 0; _i < 2; ++_i) \
;         __builtin_amdgcn_global_load_lds((const unsigned*)((const char*)(gbase) + (voff)[_i]), (PG8_LAS unsigned*)(lds + (bufoff) + ldsw + _i * 8192), 16, 0, 0); } while (0)
; #define PG8_LDA(dst, b, h) do { _Pragma("unroll") for (int m = 0; m < 4; ++m) _Pragma("unroll") for (int k = 0; k < 2; ++k) dst[m][k] = *(const PG8_LAS bf16x8*)(lds + PG8_SA(b, h) + aoff + m * 2048 + k * 1024); } while (0)
; #define PG8_LDB(dst, b, h) do { _Pragma("unroll") for (int n = 0; n < 2; ++n) _Pragma("unroll") for (int k = 0; k < 2; ++k) dst[n][k] = *(const PG8_LAS bf16x8*)(lds + PG8_SB(b, h) + boff + n * 2048 + k * 1024); } while (0)
; #define PG8_WAIT_V(n) asm volatile("s_waitcnt vmcnt(" #n ")" ::: "memory")
; #define PG8_WAIT_L(n) asm volatile("s_waitcnt lgkmcnt(" #n ")" ::: "memory")
; #define PG8_BAR __builtin_amdgcn_s_barrier()
; #define PG8_SCHED __builtin_amdgcn_sched_barrier(0)
;     ...
;         for (int t = 0; t < nt; t += 2) {
;             const bool last = (t == nt - 2);
;             const char* a1 = cA + (size_t)(t + 1) * kstep;
;             const char* a2 = last ? nA : cA + (size_t)(t + 2) * kstep; const char* b2 = last ? nB : cB + (size_t)(t + 2) * kstep;
;             const char* a3 = a2 + kstep; const char* b3 = b2 + kstep;
;             if (last && has_next) S.a_ready(nxt);
;             if constexpr (SP2) {
;             PG8_LDB(B0, 0, 0); PG8_LDB(B1, 0, 1); PG8_SCHED; PG8_LDA(At, 0, 0); PG8_STAGE(PG8_SA(1, 1), a1 + hstepA, voffA);
;             PG8_WAIT_V(8); PG8_WAIT_L(0); PG8_BAR; PG8_MMA(0, 0, At, B0); PG8_MMA(0, 1, At, B1); PG8_BAR; PG8_SCHED;
;             PG8_LDA(At, 0, 1); PG8_STAGE(PG8_SB(0, 0), b2, voffB); PG8_STAGE(PG8_SB(0, 1), b2 + hstepB, voffB); PG8_STAGE(PG8_SA(0, 0), a2, voffA);
;             PG8_WAIT_V(8); PG8_WAIT_L(0); PG8_BAR; PG8_MMA(1, 0, At, B0); PG8_MMA(1, 1, At, B1); PG8_BAR; PG8_SCHED;
.LBB0_2023:
	v_add_u32_e32 v163, 0x10000, v235
	s_add_u32 s35, s40, 0xfffc0080
	s_addc_u32 s37, s41, -1
	s_add_i32 s43, 0, 0x10000
	s_cmp_eq_u32 s34, 12
	s_cselect_b32 s57, s49, s37
	s_cselect_b32 s56, s48, s35
	s_cselect_b32 s55, s51, s24
	s_cselect_b32 s54, s50, s15
	s_add_i32 s35, 0, 0x14000
	ds_read_b128 v[142:145], v163
	ds_read_b128 v[146:149], v163 offset:1024
	ds_read_b128 v[150:153], v163 offset:2048
	ds_read_b128 v[154:157], v163 offset:3072
	ds_read_b128 v[158:161], v163 offset:16384
	ds_read_b128 v[186:189], v163 offset:17408
	ds_read_b128 v[190:193], v163 offset:18432
	ds_read_b128 v[194:197], v163 offset:19456
	s_add_i32 m0, s53, 0xc000
	ds_read_b128 v[198:201], v237
	ds_read_b128 v[202:205], v237 offset:1024
	ds_read_b128 v[206:209], v237 offset:2048
	ds_read_b128 v[210:213], v237 offset:3072
	ds_read_b128 v[214:217], v237 offset:4096
	ds_read_b128 v[218:221], v237 offset:5120
	ds_read_b128 v[222:225], v237 offset:6144
	ds_read_b128 v[238:241], v237 offset:7168
	global_load_lds_dwordx4 v138, s[40:41]
	s_add_i32 m0, s53, 0xe000
	s_nop 0
	global_load_lds_dwordx4 v140, s[40:41]
	s_waitcnt vmcnt(8)
	s_waitcnt lgkmcnt(0)
	s_barrier
	s_setprio 1
	v_mfma_f32_16x16x32_bf16 v[128:131], v[142:145], v[198:201], v[128:131]
	v_mfma_f32_16x16x32_bf16 v[124:127], v[150:153], v[198:201], v[124:127]
	v_mfma_f32_16x16x32_bf16 v[120:123], v[142:145], v[206:209], v[120:123]
	v_mfma_f32_16x16x32_bf16 v[116:119], v[150:153], v[206:209], v[116:119]
	v_mfma_f32_16x16x32_bf16 v[112:115], v[142:145], v[214:217], v[112:115]
	v_mfma_f32_16x16x32_bf16 v[108:111], v[150:153], v[214:217], v[108:111]
	v_mfma_f32_16x16x32_bf16 v[104:107], v[142:145], v[222:225], v[104:107]
	v_mfma_f32_16x16x32_bf16 v[100:103], v[150:153], v[222:225], v[100:103]
	v_mfma_f32_16x16x32_bf16 v[128:131], v[146:149], v[202:205], v[128:131]
	v_mfma_f32_16x16x32_bf16 v[124:127], v[154:157], v[202:205], v[124:127]
	v_mfma_f32_16x16x32_bf16 v[120:123], v[146:149], v[210:213], v[120:123]
	v_mfma_f32_16x16x32_bf16 v[116:119], v[154:157], v[210:213], v[116:119]
	v_mfma_f32_16x16x32_bf16 v[112:115], v[146:149], v[218:221], v[112:115]
	v_mfma_f32_16x16x32_bf16 v[108:111], v[154:157], v[218:221], v[108:111]
	v_mfma_f32_16x16x32_bf16 v[104:107], v[146:149], v[238:241], v[104:107]
	v_mfma_f32_16x16x32_bf16 v[100:103], v[154:157], v[238:241], v[100:103]
	v_mfma_f32_16x16x32_bf16 v[96:99], v[158:161], v[198:201], v[96:99]
	v_mfma_f32_16x16x32_bf16 v[92:95], v[190:193], v[198:201], v[92:95]
	v_mfma_f32_16x16x32_bf16 v[88:91], v[158:161], v[206:209], v[88:91]
	v_mfma_f32_16x16x32_bf16 v[84:87], v[190:193], v[206:209], v[84:87]
	v_mfma_f32_16x16x32_bf16 v[80:83], v[158:161], v[214:217], v[80:83]
	v_mfma_f32_16x16x32_bf16 v[76:79], v[190:193], v[214:217], v[76:79]
	v_mfma_f32_16x16x32_bf16 v[72:75], v[158:161], v[222:225], v[72:75]
	v_mfma_f32_16x16x32_bf16 v[68:71], v[190:193], v[222:225], v[68:71]
	v_mfma_f32_16x16x32_bf16 v[96:99], v[186:189], v[202:205], v[96:99]
	v_mfma_f32_16x16x32_bf16 v[92:95], v[194:197], v[202:205], v[92:95]
	v_mfma_f32_16x16x32_bf16 v[88:91], v[186:189], v[210:213], v[88:91]
	v_mfma_f32_16x16x32_bf16 v[84:87], v[194:197], v[210:213], v[84:87]
	v_mfma_f32_16x16x32_bf16 v[80:83], v[186:189], v[218:221], v[80:83]
	v_mfma_f32_16x16x32_bf16 v[76:79], v[194:197], v[218:221], v[76:79]
	v_mfma_f32_16x16x32_bf16 v[72:75], v[186:189], v[238:241], v[72:75]
	v_mfma_f32_16x16x32_bf16 v[68:71], v[194:197], v[238:241], v[68:71]
	s_setprio 0
	s_barrier
	s_add_i32 s37, s43, s21
	s_mov_b32 m0, s37
	ds_read_b128 v[198:201], v237 offset:16384
	ds_read_b128 v[202:205], v237 offset:17408
	ds_read_b128 v[206:209], v237 offset:18432
	ds_read_b128 v[210:213], v237 offset:19456
	ds_read_b128 v[214:217], v237 offset:20480
	ds_read_b128 v[218:221], v237 offset:21504
	ds_read_b128 v[222:225], v237 offset:22528
	ds_read_b128 v[238:241], v237 offset:23552
	global_load_lds_dwordx4 v34, s[54:55]
	s_add_i32 m0, s37, 0x2000
	s_add_u32 s66, s54, 0x40000
	s_addc_u32 s67, s55, 0
	s_add_i32 s35, s35, s21
	global_load_lds_dwordx4 v136, s[54:55]
	s_mov_b32 m0, s35
	s_nop 0
	global_load_lds_dwordx4 v34, s[66:67]
	s_add_i32 m0, s35, 0x2000
	s_nop 0
	global_load_lds_dwordx4 v136, s[66:67]
	s_mov_b32 m0, s53
	s_nop 0
	global_load_lds_dwordx4 v132, s[56:57]
	s_mov_b32 m0, s58
	s_nop 0
	global_load_lds_dwordx4 v134, s[56:57]
	s_waitcnt vmcnt(8)
	s_waitcnt lgkmcnt(0)
	s_barrier
	s_setprio 1
	v_mfma_f32_16x16x32_bf16 v[64:67], v[142:145], v[198:201], v[64:67]
	v_mfma_f32_16x16x32_bf16 v[60:63], v[150:153], v[198:201], v[60:63]
	v_mfma_f32_16x16x32_bf16 v[56:59], v[142:145], v[206:209], v[56:59]
	v_mfma_f32_16x16x32_bf16 v[52:55], v[150:153], v[206:209], v[52:55]
	v_mfma_f32_16x16x32_bf16 v[48:51], v[142:145], v[214:217], v[48:51]
	v_mfma_f32_16x16x32_bf16 v[44:47], v[150:153], v[214:217], v[44:47]
	v_mfma_f32_16x16x32_bf16 v[40:43], v[142:145], v[222:225], v[40:43]
	v_mfma_f32_16x16x32_bf16 v[36:39], v[150:153], v[222:225], v[36:39]
	v_mfma_f32_16x16x32_bf16 v[64:67], v[146:149], v[202:205], v[64:67]
	v_mfma_f32_16x16x32_bf16 v[60:63], v[154:157], v[202:205], v[60:63]
	v_mfma_f32_16x16x32_bf16 v[56:59], v[146:149], v[210:213], v[56:59]
	v_mfma_f32_16x16x32_bf16 v[52:55], v[154:157], v[210:213], v[52:55]
	v_mfma_f32_16x16x32_bf16 v[48:51], v[146:149], v[218:221], v[48:51]
	v_mfma_f32_16x16x32_bf16 v[44:47], v[154:157], v[218:221], v[44:47]
	v_mfma_f32_16x16x32_bf16 v[40:43], v[146:149], v[238:241], v[40:43]
	v_mfma_f32_16x16x32_bf16 v[36:39], v[154:157], v[238:241], v[36:39]
	v_mfma_f32_16x16x32_bf16 v[30:33], v[158:161], v[198:201], v[30:33]
	v_mfma_f32_16x16x32_bf16 v[26:29], v[190:193], v[198:201], v[26:29]
	v_mfma_f32_16x16x32_bf16 v[22:25], v[158:161], v[206:209], v[22:25]
	v_mfma_f32_16x16x32_bf16 v[18:21], v[190:193], v[206:209], v[18:21]
	v_mfma_f32_16x16x32_bf16 v[14:17], v[158:161], v[214:217], v[14:17]
	v_mfma_f32_16x16x32_bf16 v[10:13], v[190:193], v[214:217], v[10:13]
	v_mfma_f32_16x16x32_bf16 v[6:9], v[158:161], v[222:225], v[6:9]
	v_mfma_f32_16x16x32_bf16 v[2:5], v[190:193], v[222:225], v[2:5]
	v_mfma_f32_16x16x32_bf16 v[30:33], v[186:189], v[202:205], v[30:33]
	v_mfma_f32_16x16x32_bf16 v[26:29], v[194:197], v[202:205], v[26:29]
	v_mfma_f32_16x16x32_bf16 v[22:25], v[186:189], v[210:213], v[22:25]
	v_mfma_f32_16x16x32_bf16 v[18:21], v[194:197], v[210:213], v[18:21]
	v_mfma_f32_16x16x32_bf16 v[14:17], v[186:189], v[218:221], v[14:17]
	v_mfma_f32_16x16x32_bf16 v[10:13], v[194:197], v[218:221], v[10:13]
	v_mfma_f32_16x16x32_bf16 v[6:9], v[186:189], v[238:241], v[6:9]
	v_mfma_f32_16x16x32_bf16 v[2:5], v[194:197], v[238:241], v[2:5]
	s_setprio 0
	s_barrier
; #define PG8_STAGE(bufoff, gbase, voff) do { _Pragma("unroll") for (int _i = 0; _i < 2; ++_i) \
;         __builtin_amdgcn_global_load_lds((const unsigned*)((const char*)(gbase) + (voff)[_i]), (PG8_LAS unsigned*)(lds + (bufoff) + ldsw + _i * 8192), 16, 0, 0); } while (0)
; #define PG8_LDA(dst, b, h) do { _Pragma("unroll") for (int m = 0; m < 4; ++m) _Pragma("unroll") for (int k = 0; k < 2; ++k) dst[m][k] = *(const PG8_LAS bf16x8*)(lds + PG8_SA(b, h) + aoff + m * 2048 + k * 1024); } while (0)
; #define PG8_LDB(dst, b, h) do { _Pragma("unroll") for (int n = 0; n < 2; ++n) _Pragma("unroll") for (int k = 0; k < 2; ++k) dst[n][k] = *(const PG8_LAS bf16x8*)(lds + PG8_SB(b, h) + boff + n * 2048 + k * 1024); } while (0)
; #define PG8_WAIT_V(n) asm volatile("s_waitcnt vmcnt(" #n ")" ::: "memory")
; #define PG8_WAIT_L(n) asm volatile("s_waitcnt lgkmcnt(" #n ")" ::: "memory")
; #define PG8_BAR __builtin_amdgcn_s_barrier()
; #define PG8_SCHED __builtin_amdgcn_sched_barrier(0)
;     ...
;         for (int t = 0; t < nt; t += 2) {
;             const bool last = (t == nt - 2);
;             const char* a1 = cA + (size_t)(t + 1) * kstep;
;             const char* a2 = last ? nA : cA + (size_t)(t + 2) * kstep; const char* b2 = last ? nB : cB + (size_t)(t + 2) * kstep;
;     ...
;             PG8_LDB(B0, 1, 0); PG8_LDB(B1, 1, 1); PG8_SCHED; PG8_LDA(At, 1, 0); PG8_STAGE(PG8_SA(0, 1), a2 + hstepA, voffA);
;             PG8_WAIT_V(8); PG8_WAIT_L(0); PG8_BAR; PG8_MMA(0, 0, At, B0); PG8_MMA(0, 1, At, B1); PG8_BAR; PG8_SCHED;
;             PG8_LDA(At, 1, 1); PG8_STAGE(PG8_SB(1, 0), b3, voffB); PG8_STAGE(PG8_SB(1, 1), b3 + hstepB, voffB); PG8_STAGE(PG8_SA(1, 0), a3, voffA);
;             PG8_WAIT_V(8); PG8_WAIT_L(0); PG8_BAR; PG8_MMA(1, 0, At, B0); PG8_MMA(1, 1, At, B1); PG8_BAR; PG8_SCHED;
	s_add_i32 s35, 0, 0x18000
	s_add_i32 s37, 0, 0x1c000
	ds_read_b128 v[142:145], v163 offset:32768
	ds_read_b128 v[146:149], v163 offset:33792
	ds_read_b128 v[150:153], v163 offset:34816
	ds_read_b128 v[154:157], v163 offset:35840
	ds_read_b128 v[158:161], v163 offset:49152
	ds_read_b128 v[186:189], v163 offset:50176
	ds_read_b128 v[190:193], v163 offset:51200
	ds_read_b128 v[194:197], v163 offset:52224
	s_add_u32 s56, s56, 0x40000
	s_addc_u32 s57, s57, 0
	s_mov_b32 m0, s59
	ds_read_b128 v[198:201], v237 offset:32768
	ds_read_b128 v[202:205], v237 offset:33792
	ds_read_b128 v[206:209], v237 offset:34816
	ds_read_b128 v[210:213], v237 offset:35840
	ds_read_b128 v[214:217], v237 offset:36864
	ds_read_b128 v[218:221], v237 offset:37888
	ds_read_b128 v[222:225], v237 offset:38912
	ds_read_b128 v[238:241], v237 offset:39936
	global_load_lds_dwordx4 v132, s[56:57]
	s_mov_b32 m0, s60
	s_nop 0
	global_load_lds_dwordx4 v134, s[56:57]
	s_waitcnt vmcnt(8)
	s_waitcnt lgkmcnt(0)
	s_barrier
	s_setprio 1
	v_mfma_f32_16x16x32_bf16 v[128:131], v[142:145], v[198:201], v[128:131]
	v_mfma_f32_16x16x32_bf16 v[124:127], v[150:153], v[198:201], v[124:127]
	v_mfma_f32_16x16x32_bf16 v[120:123], v[142:145], v[206:209], v[120:123]
	v_mfma_f32_16x16x32_bf16 v[116:119], v[150:153], v[206:209], v[116:119]
	v_mfma_f32_16x16x32_bf16 v[112:115], v[142:145], v[214:217], v[112:115]
	v_mfma_f32_16x16x32_bf16 v[108:111], v[150:153], v[214:217], v[108:111]
	v_mfma_f32_16x16x32_bf16 v[104:107], v[142:145], v[222:225], v[104:107]
	v_mfma_f32_16x16x32_bf16 v[100:103], v[150:153], v[222:225], v[100:103]
	v_mfma_f32_16x16x32_bf16 v[128:131], v[146:149], v[202:205], v[128:131]
	v_mfma_f32_16x16x32_bf16 v[124:127], v[154:157], v[202:205], v[124:127]
	v_mfma_f32_16x16x32_bf16 v[120:123], v[146:149], v[210:213], v[120:123]
	v_mfma_f32_16x16x32_bf16 v[116:119], v[154:157], v[210:213], v[116:119]
	v_mfma_f32_16x16x32_bf16 v[112:115], v[146:149], v[218:221], v[112:115]
	v_mfma_f32_16x16x32_bf16 v[108:111], v[154:157], v[218:221], v[108:111]
	v_mfma_f32_16x16x32_bf16 v[104:107], v[146:149], v[238:241], v[104:107]
	v_mfma_f32_16x16x32_bf16 v[100:103], v[154:157], v[238:241], v[100:103]
	v_mfma_f32_16x16x32_bf16 v[96:99], v[158:161], v[198:201], v[96:99]
	v_mfma_f32_16x16x32_bf16 v[92:95], v[190:193], v[198:201], v[92:95]
	v_mfma_f32_16x16x32_bf16 v[88:91], v[158:161], v[206:209], v[88:91]
	v_mfma_f32_16x16x32_bf16 v[84:87], v[190:193], v[206:209], v[84:87]
	v_mfma_f32_16x16x32_bf16 v[80:83], v[158:161], v[214:217], v[80:83]
	v_mfma_f32_16x16x32_bf16 v[76:79], v[190:193], v[214:217], v[76:79]
	v_mfma_f32_16x16x32_bf16 v[72:75], v[158:161], v[222:225], v[72:75]
	v_mfma_f32_16x16x32_bf16 v[68:71], v[190:193], v[222:225], v[68:71]
	v_mfma_f32_16x16x32_bf16 v[96:99], v[186:189], v[202:205], v[96:99]
	v_mfma_f32_16x16x32_bf16 v[92:95], v[194:197], v[202:205], v[92:95]
	v_mfma_f32_16x16x32_bf16 v[88:91], v[186:189], v[210:213], v[88:91]
	v_mfma_f32_16x16x32_bf16 v[84:87], v[194:197], v[210:213], v[84:87]
	v_mfma_f32_16x16x32_bf16 v[80:83], v[186:189], v[218:221], v[80:83]
	v_mfma_f32_16x16x32_bf16 v[76:79], v[194:197], v[218:221], v[76:79]
	v_mfma_f32_16x16x32_bf16 v[72:75], v[186:189], v[238:241], v[72:75]
	v_mfma_f32_16x16x32_bf16 v[68:71], v[194:197], v[238:241], v[68:71]
	s_setprio 0
	s_barrier
	s_add_i32 s35, s35, s21
	s_mov_b32 m0, s35
	ds_read_b128 v[198:201], v237 offset:49152
	ds_read_b128 v[202:205], v237 offset:50176
	ds_read_b128 v[206:209], v237 offset:51200
	ds_read_b128 v[210:213], v237 offset:52224
	ds_read_b128 v[214:217], v237 offset:53248
	ds_read_b128 v[218:221], v237 offset:54272
	ds_read_b128 v[222:225], v237 offset:55296
	ds_read_b128 v[238:241], v237 offset:56320
	s_add_u32 vcc_lo, s54, 0x80
	s_addc_u32 vcc_hi, s55, 0
	global_load_lds_dwordx4 v34, vcc
	s_add_i32 m0, s35, 0x2000
	s_add_u32 s54, s54, 0x40080
	s_addc_u32 s55, s55, 0
	s_add_i32 s35, s37, s21
	s_add_u32 vcc_lo, s54, 0xfffc0000
	s_addc_u32 vcc_hi, s55, -1
	global_load_lds_dwordx4 v136, vcc
	s_mov_b32 m0, s35
	s_nop 0
	global_load_lds_dwordx4 v34, s[54:55]
	s_add_i32 m0, s35, 0x2000
	s_nop 0
	global_load_lds_dwordx4 v136, s[54:55]
	s_mov_b32 m0, s61
	s_add_u32 vcc_lo, s56, 0xfffc0080
	s_addc_u32 vcc_hi, s57, -1
	global_load_lds_dwordx4 v132, vcc
	s_mov_b32 m0, s62
	s_nop 0
	global_load_lds_dwordx4 v134, vcc
	s_waitcnt vmcnt(8)
	s_waitcnt lgkmcnt(0)
	s_barrier
	s_setprio 1
	v_mfma_f32_16x16x32_bf16 v[64:67], v[142:145], v[198:201], v[64:67]
	v_mfma_f32_16x16x32_bf16 v[60:63], v[150:153], v[198:201], v[60:63]
	v_mfma_f32_16x16x32_bf16 v[56:59], v[142:145], v[206:209], v[56:59]
	v_mfma_f32_16x16x32_bf16 v[52:55], v[150:153], v[206:209], v[52:55]
	v_mfma_f32_16x16x32_bf16 v[48:51], v[142:145], v[214:217], v[48:51]
	v_mfma_f32_16x16x32_bf16 v[44:47], v[150:153], v[214:217], v[44:47]
	v_mfma_f32_16x16x32_bf16 v[40:43], v[142:145], v[222:225], v[40:43]
	v_mfma_f32_16x16x32_bf16 v[36:39], v[150:153], v[222:225], v[36:39]
	v_mfma_f32_16x16x32_bf16 v[64:67], v[146:149], v[202:205], v[64:67]
	v_mfma_f32_16x16x32_bf16 v[60:63], v[154:157], v[202:205], v[60:63]
	v_mfma_f32_16x16x32_bf16 v[56:59], v[146:149], v[210:213], v[56:59]
	v_mfma_f32_16x16x32_bf16 v[52:55], v[154:157], v[210:213], v[52:55]
	v_mfma_f32_16x16x32_bf16 v[48:51], v[146:149], v[218:221], v[48:51]
	v_mfma_f32_16x16x32_bf16 v[44:47], v[154:157], v[218:221], v[44:47]
	v_mfma_f32_16x16x32_bf16 v[40:43], v[146:149], v[238:241], v[40:43]
	v_mfma_f32_16x16x32_bf16 v[36:39], v[154:157], v[238:241], v[36:39]
	v_mfma_f32_16x16x32_bf16 v[30:33], v[158:161], v[198:201], v[30:33]
	v_mfma_f32_16x16x32_bf16 v[26:29], v[190:193], v[198:201], v[26:29]
	v_mfma_f32_16x16x32_bf16 v[22:25], v[158:161], v[206:209], v[22:25]
	v_mfma_f32_16x16x32_bf16 v[18:21], v[190:193], v[206:209], v[18:21]
	v_mfma_f32_16x16x32_bf16 v[14:17], v[158:161], v[214:217], v[14:17]
	v_mfma_f32_16x16x32_bf16 v[10:13], v[190:193], v[214:217], v[10:13]
	v_mfma_f32_16x16x32_bf16 v[6:9], v[158:161], v[222:225], v[6:9]
	v_mfma_f32_16x16x32_bf16 v[2:5], v[190:193], v[222:225], v[2:5]
	v_mfma_f32_16x16x32_bf16 v[30:33], v[186:189], v[202:205], v[30:33]
	v_mfma_f32_16x16x32_bf16 v[26:29], v[194:197], v[202:205], v[26:29]
	v_mfma_f32_16x16x32_bf16 v[22:25], v[186:189], v[210:213], v[22:25]
	v_mfma_f32_16x16x32_bf16 v[18:21], v[194:197], v[210:213], v[18:21]
	v_mfma_f32_16x16x32_bf16 v[14:17], v[186:189], v[218:221], v[14:17]
	v_mfma_f32_16x16x32_bf16 v[10:13], v[194:197], v[218:221], v[10:13]
	v_mfma_f32_16x16x32_bf16 v[6:9], v[186:189], v[238:241], v[6:9]
	v_mfma_f32_16x16x32_bf16 v[2:5], v[194:197], v[238:241], v[2:5]
	s_setprio 0
	s_barrier
	s_add_i32 s34, s34, 2
	s_add_u32 s40, s40, 0x100
	s_addc_u32 s41, s41, 0
	s_add_u32 s15, s15, 0x100
	s_addc_u32 s24, s24, 0
	s_cmp_gt_u32 s34, 13
	s_cbranch_scc0 .LBB0_2023
	s_and_b64 vcc, exec, s[30:31]
	s_cbranch_vccz .LBB0_2026
	s_barrier
